# M1 DN column-sum unrolled with all LDS reads up front and packed adds, plus shared gate cumsum M1 to M3 and permlane swaps in P2/P7 epilogues
# baseline (speedup 1.0000x reference)
; __device__ __forceinline__ unsigned cvt_pk_bf16(float lo, float hi) { unsigned r; asm volatile("v_cvt_pk_bf16_f32 %0, %1, %2" : "=v"(r) : "v"(lo), "v"(hi)); return r; }
;     __device__ __forceinline__ void operator()(const f32x4 (&acc)[2][2][4][2], const Unit& u, int wr, int wc, int fr, int fq) const {
;     ...
;                 const int row = row0 + ai * HALF + m * 16; const size_t off = (size_t)row * DM + col0; float q = 0.f;
; #pragma unroll
;                 for (int bj = 0; bj < 2; ++bj) {
;                     const size_t o2 = off + bj * HALF; f32x4 b0, b1;
;                     if (XI_BF16) bf8_to_f32(xin[0][m][bj], b0, b1); else { b0 = *(const f32x4*)(xi + o2); b1 = *(const f32x4*)(xi + o2 + 4); }
;                     const f32x4 o0 = b0 + acc[ai][bj][m][0] * scale, o1 = b1 + acc[ai][bj][m][1] * scale;
;                     u32x4 w; w.x = cvt_pk_bf16(o0[0], o0[1]); w.y = cvt_pk_bf16(o0[2], o0[3]); w.z = cvt_pk_bf16(o1[0], o1[1]); w.w = cvt_pk_bf16(o1[2], o1[3]);
;                     *(u32x4*)(xb + o2) = w;
;                     q += ((o0[0] * o0[0] + o0[1] * o0[1]) + (o0[2] * o0[2] + o0[3] * o0[3])) + ((o1[0] * o1[0] + o1[1] * o1[1]) + (o1[2] * o1[2] + o1[3] * o1[3]));
;                 }
;                 q += __shfl_xor(q, 16); q += __shfl_xor(q, 32);
;                 if (fq == 0) ssout[(size_t)row * 16 + u.pn * 4 + wc] = q;
.Lalign_p2:
	v_and_b32_e32 v217, 64, v203
	v_xor_b32_e32 v216, 16, v203
	v_add_u32_e32 v217, 64, v217
	v_xor_b32_e32 v218, 32, v203
	v_cmp_lt_i32_e32 vcc, v216, v217
	s_lshl_b32 s20, s4, 2
	s_ashr_i32 s21, s20, 31
	v_cndmask_b32_e32 v219, v203, v216, vcc
	v_cmp_lt_i32_e32 vcc, v218, v217
	v_lshl_add_u64 v[216:217], s[76:77], 0, v[204:205]
	v_lshlrev_b32_e32 v204, 2, v219
	v_cndmask_b32_e32 v224, v203, v218, vcc
	v_lshl_add_u64 v[214:215], v[216:217], 0, v[214:215]
	s_waitcnt vmcnt(0)
	v_lshlrev_b32_e32 v216, 16, v206
	v_and_b32_e32 v217, 0xffff0000, v206
	v_lshlrev_b32_e32 v206, 16, v207
	v_and_b32_e32 v207, 0xffff0000, v207
	v_lshlrev_b32_e32 v218, 16, v208
	v_and_b32_e32 v219, 0xffff0000, v208
	v_lshlrev_b32_e32 v208, 16, v209
	v_and_b32_e32 v209, 0xffff0000, v209
	v_lshlrev_b32_e32 v220, 16, v210
	v_and_b32_e32 v221, 0xffff0000, v210
	v_lshlrev_b32_e32 v210, 16, v211
	v_and_b32_e32 v211, 0xffff0000, v211
	v_lshlrev_b32_e32 v222, 16, v212
	v_and_b32_e32 v223, 0xffff0000, v212
	v_lshlrev_b32_e32 v212, 16, v213
	v_and_b32_e32 v213, 0xffff0000, v213
	v_pk_fma_f32 v[126:127], v[126:127], 0.5, v[206:207] op_sel_hi:[1,0,1]
	v_pk_fma_f32 v[124:125], v[124:125], 0.5, v[216:217] op_sel_hi:[1,0,1]
	v_pk_fma_f32 v[122:123], v[122:123], 0.5, v[208:209] op_sel_hi:[1,0,1]
	v_pk_fma_f32 v[120:121], v[120:121], 0.5, v[218:219] op_sel_hi:[1,0,1]
	v_pk_fma_f32 v[118:119], v[118:119], 0.5, v[210:211] op_sel_hi:[1,0,1]
	v_pk_fma_f32 v[116:117], v[116:117], 0.5, v[220:221] op_sel_hi:[1,0,1]
	v_pk_fma_f32 v[206:207], v[114:115], 0.5, v[212:213] op_sel_hi:[1,0,1]
	v_pk_fma_f32 v[208:209], v[112:113], 0.5, v[222:223] op_sel_hi:[1,0,1]
	v_cvt_pk_bf16_f32 v112, v124, v125
	v_cvt_pk_bf16_f32 v113, v126, v127
	v_mul_f32_e32 v114, v125, v125
	v_mul_f32_e32 v115, v127, v127
	v_mul_f32_e32 v125, v121, v121
	v_mul_f32_e32 v127, v123, v123
	v_mul_f32_e32 v205, v117, v117
	v_mul_f32_e32 v210, v119, v119
	v_mul_f32_e32 v211, v209, v209
	v_mul_f32_e32 v212, v207, v207
	v_fmac_f32_e32 v114, v124, v124
	v_fmac_f32_e32 v115, v126, v126
	v_fmac_f32_e32 v125, v120, v120
	v_fmac_f32_e32 v127, v122, v122
	v_fmac_f32_e32 v205, v116, v116
	v_fmac_f32_e32 v210, v118, v118
	v_fmac_f32_e32 v211, v208, v208
	v_fmac_f32_e32 v212, v206, v206
	v_add_f32_e32 v114, v114, v115
	v_add_f32_e32 v115, v125, v127
	v_add_f32_e32 v124, v205, v210
	v_add_f32_e32 v125, v211, v212
	v_add_f32_e32 v114, v114, v115
	v_add_f32_e32 v115, v124, v125
	v_add_f32_e32 v124, v114, v115
	v_mov_b32_e32 v125, v124
	s_nop 1
	v_permlane16_swap_b32_e32 v124, v125
	v_cvt_pk_bf16_f32 v114, v120, v121
	v_cvt_pk_bf16_f32 v115, v122, v123
	global_store_dwordx4 v[214:215], v[112:115], off
	v_cvt_pk_bf16_f32 v116, v116, v117
	v_cvt_pk_bf16_f32 v117, v118, v119
	v_cvt_pk_bf16_f32 v118, v208, v209
	v_cvt_pk_bf16_f32 v119, v206, v207
	global_store_dwordx4 v[214:215], v[116:119], off offset:256
	s_waitcnt lgkmcnt(0)
	v_add_f32_e32 v113, v124, v125
	v_lshlrev_b32_e32 v112, 2, v224
	v_mov_b32_e32 v114, v113
	s_nop 1
	v_permlane32_swap_b32_e32 v113, v114
	s_and_saveexec_b64 s[24:25], s[8:9]
	s_cbranch_execz .LBB0_377
	v_lshlrev_b64 v[116:117], 6, v[188:189]
	v_lshl_add_u64 v[116:117], s[14:15], 0, v[116:117]
	v_lshl_add_u64 v[116:117], s[20:21], 2, v[116:117]
	s_lshl_b32 s4, s34, 2
	v_lshl_add_u64 v[116:117], v[116:117], 0, s[4:5]
	s_waitcnt lgkmcnt(0)
	v_add_f32_e32 v113, v113, v114
	global_store_dword v[116:117], v113, off

; __device__ __forceinline__ u32x4 pack8(const float (&v)[8]) { u32x4 o; o.x = pk2(v[0], v[1]); o.y = pk2(v[2], v[3]); o.z = pk2(v[4], v[5]); o.w = pk2(v[6], v[7]); return o; }
; __device__ __forceinline__ void conv4x8(const bf16* proj, int t, int ch, const float* cw, const float* cb, float sc, float (&o)[4][8]) {
;     u32x4 raw[7];
; #pragma unroll
;     for (int i = 0; i < 7; ++i) { const int tr = t - 3 + i; raw[i] = tr >= 0 ? *(const u32x4*)(proj + (size_t)tr * NPROJ + ch) : (u32x4){0u, 0u, 0u, 0u}; }
;     { const f32x4 b0 = *(const f32x4*)(cb + ch), b1 = *(const f32x4*)(cb + ch + 4);
; #pragma unroll
;       for (int j = 0; j < 4; ++j) { o[j][0] = b0[0]; o[j][1] = b0[1]; o[j][2] = b0[2]; o[j][3] = b0[3]; o[j][4] = b1[0]; o[j][5] = b1[1]; o[j][6] = b1[2]; o[j][7] = b1[3]; } }
; #pragma unroll
;     for (int w = 0; w < 4; ++w) {
;         const f32x4 w0 = *(const f32x4*)(cw + w * 1024 + ch), w1 = *(const f32x4*)(cw + w * 1024 + ch + 4);
;         const float wv[8] = {w0[0], w0[1], w0[2], w0[3], w1[0], w1[1], w1[2], w1[3]};
; #pragma unroll
;         for (int j = 0; j < 4; ++j) { float xv[8]; unpack8(raw[j + w], xv);
; #pragma unroll
;             for (int e = 0; e < 8; ++e) o[j][e] += wv[e] * xv[e]; }
;     }
; #pragma unroll
;     for (int j = 0; j < 4; ++j)
; #pragma unroll
;         for (int e = 0; e < 8; ++e) o[j][e] = o[j][e] * sc * __builtin_amdgcn_rcpf(1.0f + __expf(-o[j][e]));
; }
; __device__ __forceinline__ void m1_phase(const Params& p, unsigned char* ldsg, int G) {
;     ...
;             conv4x8(PROJ, t0 + l0, h * HD + cgp * 8, p.convw, p.convb, 1.0f, qv);
; #pragma unroll
;             for (int j = 0; j < 4; ++j) *(u32x4*)(QKC + (size_t)(t0 + l0 + j) * DM + h * HD + cgp * 8) = pack8(qv[j]);
;         }
;         asm volatile("" ::: "memory");
;         conv4x8(PROJ, t0 + l0, 512 + h * HD + cgp * 8, p.convw, p.convb, 0.08838834764831845f, kk);
; #pragma unroll
;         for (int j = 0; j < 4; ++j) *(u32x4*)(QKC + (size_t)(t0 + l0 + j) * DM + 512 + h * HD + cgp * 8) = pack8(kk[j]);
;         {
;             u32x4 rv[4];
; #pragma unroll
;             for (int j = 0; j < 4; ++j) rv[j] = *(const u32x4*)(PROJ + (size_t)(t0 + l0 + j) * NPROJ + 1024 + h * HD + cgp * 8);
.LBB0_630:
	s_or_b64 exec, exec, s[0:1]
	v_lshlrev_b64 v[10:11], 2, v[6:7]
	v_lshl_add_u64 v[12:13], s[50:51], 0, v[10:11]
	v_lshl_add_u64 v[42:43], s[48:49], 0, v[10:11]
	global_load_dwordx4 v[6:9], v[12:13], off offset:16
	global_load_dwordx4 v[14:17], v[12:13], off
	s_nop 0
	global_load_dwordx4 v[10:13], v[42:43], off offset:16
	global_load_dwordx4 v[18:21], v[42:43], off
	s_waitcnt vmcnt(4)
	v_lshlrev_b32_e32 v98, 16, v26
	v_and_b32_e32 v100, 0xffff0000, v26
	v_add_co_u32_e64 v26, s[0:1], s65, v42
	v_lshlrev_b32_e32 v99, 16, v27
	v_and_b32_e32 v101, 0xffff0000, v27
	v_lshlrev_b32_e32 v96, 16, v22
	v_and_b32_e32 v94, 0xffff0000, v22
	v_lshlrev_b32_e32 v97, 16, v23
	v_and_b32_e32 v95, 0xffff0000, v23
	v_lshl_add_u64 v[22:23], v[42:43], 0, s[6:7]
	v_addc_co_u32_e64 v27, s[0:1], 0, v43, s[0:1]
	v_lshlrev_b32_e32 v103, 16, v29
	v_lshlrev_b32_e32 v102, 16, v28
	v_and_b32_e32 v83, 0xffff0000, v29
	v_and_b32_e32 v82, 0xffff0000, v28
	v_lshlrev_b32_e32 v90, 16, v24
	v_and_b32_e32 v84, 0xffff0000, v24
	v_lshlrev_b32_e32 v91, 16, v25
	v_and_b32_e32 v85, 0xffff0000, v25
	global_load_dwordx4 v[34:37], v[26:27], off offset:-4096
	s_nop 0
	global_load_dwordx4 v[22:25], v[22:23], off offset:16
	v_lshl_add_u64 v[28:29], v[42:43], 0, s[38:39]
	v_lshl_add_u64 v[44:45], v[42:43], 0, s[40:41]
	v_add_co_u32_e64 v42, s[0:1], s80, v42
	global_load_dwordx4 v[38:41], v[26:27], off
	s_nop 0
	global_load_dwordx4 v[26:29], v[28:29], off offset:16
	v_addc_co_u32_e64 v43, s[0:1], 0, v43, s[0:1]
	global_load_dwordx4 v[46:49], v[42:43], off
	s_nop 0
	global_load_dwordx4 v[42:45], v[44:45], off offset:16
	s_ashr_i32 s59, s58, 31
	v_lshl_add_u64 v[62:63], s[58:59], 1, v[68:69]
	v_add_u32_e32 v248, s58, v119
	v_ashrrev_i32_e32 v249, 31, v248
	v_lshl_add_u64 v[248:249], v[248:249], 1, s[78:79]
	v_cmp_lt_i32_e64 s[98:99], 2, v74
	v_mov_b32_e32 v188, 0
	v_mov_b32_e32 v189, 0
	v_mov_b32_e32 v190, 0
	v_mov_b32_e32 v191, 0
	v_mov_b32_e32 v192, 0
	v_mov_b32_e32 v193, 0
	v_mov_b32_e32 v194, 0
	v_mov_b32_e32 v195, 0
	v_mov_b32_e32 v196, 0
	v_mov_b32_e32 v197, 0
	v_mov_b32_e32 v198, 0
	v_mov_b32_e32 v199, 0
	v_mov_b32_e32 v200, 0
	v_mov_b32_e32 v201, 0
	v_mov_b32_e32 v202, 0
	v_mov_b32_e32 v203, 0
	v_mov_b32_e32 v204, 0
	v_mov_b32_e32 v205, 0
	v_mov_b32_e32 v206, 0
	v_mov_b32_e32 v207, 0
	v_mov_b32_e32 v208, 0
	v_mov_b32_e32 v209, 0
	v_mov_b32_e32 v210, 0
	v_mov_b32_e32 v211, 0
	v_mov_b32_e32 v212, 0
	v_mov_b32_e32 v213, 0
	v_mov_b32_e32 v214, 0
	v_mov_b32_e32 v215, 0
	s_and_saveexec_b64 s[100:101], s[98:99]
	v_mad_u64_u32 v[238:239], s[84:85], v110, s63, v[248:249]
	global_load_dwordx4 v[188:191], v[238:239], off
	s_or_b64 exec, exec, s[100:101]
	s_and_saveexec_b64 s[100:101], s[22:23]
	v_mad_u64_u32 v[238:239], s[84:85], v111, s63, v[248:249]
	global_load_dwordx4 v[192:195], v[238:239], off
	s_or_b64 exec, exec, s[100:101]
	s_and_saveexec_b64 s[100:101], s[24:25]
	v_mad_u64_u32 v[238:239], s[84:85], v112, s63, v[248:249]
	global_load_dwordx4 v[196:199], v[238:239], off
	s_or_b64 exec, exec, s[100:101]
	s_and_saveexec_b64 s[100:101], s[60:61]
	v_mad_u64_u32 v[238:239], s[84:85], v74, s63, v[248:249]
	global_load_dwordx4 v[200:203], v[238:239], off
	s_or_b64 exec, exec, s[100:101]
	s_and_saveexec_b64 s[100:101], s[26:27]
	v_mad_u64_u32 v[238:239], s[84:85], v76, s63, v[248:249]
	global_load_dwordx4 v[204:207], v[238:239], off
	s_or_b64 exec, exec, s[100:101]
	s_and_saveexec_b64 s[100:101], s[28:29]
	v_mad_u64_u32 v[238:239], s[84:85], v78, s63, v[248:249]
	global_load_dwordx4 v[208:211], v[238:239], off
	s_or_b64 exec, exec, s[100:101]
	s_and_saveexec_b64 s[100:101], s[30:31]
	v_mad_u64_u32 v[238:239], s[84:85], v80, s63, v[248:249]
	global_load_dwordx4 v[212:215], v[238:239], off
	s_or_b64 exec, exec, s[100:101]
	v_lshl_add_u64 v[248:249], s[58:59], 1, v[66:67]
	v_lshl_add_u64 v[248:249], v[248:249], 0, s[78:79]
	v_mad_u64_u32 v[238:239], s[84:85], v74, s63, v[248:249]
	global_load_dwordx4 v[216:219], v[238:239], off offset:2048
	v_mad_u64_u32 v[238:239], s[84:85], v76, s63, v[248:249]
	global_load_dwordx4 v[220:223], v[238:239], off offset:2048
	v_mad_u64_u32 v[238:239], s[84:85], v78, s63, v[248:249]
	global_load_dwordx4 v[224:227], v[238:239], off offset:2048
	v_mad_u64_u32 v[238:239], s[84:85], v80, s63, v[248:249]
	global_load_dwordx4 v[250:253], v[238:239], off offset:2048
	s_waitcnt vmcnt(19)
	v_mov_b32_e32 v88, v14
	s_waitcnt vmcnt(17)
	v_mov_b32_e32 v86, v18
	v_mov_b32_e32 v87, v20
	v_mov_b32_e32 v89, v16
	v_mov_b32_e32 v20, v19
	v_mov_b32_e32 v16, v15
	v_pk_fma_f32 v[104:105], v[86:87], v[98:99], v[88:89]
	v_pk_fma_f32 v[106:107], v[20:21], v[100:101], v[16:17]
	v_lshlrev_b32_e32 v99, 16, v55
	v_lshlrev_b32_e32 v98, 16, v54
	v_and_b32_e32 v101, 0xffff0000, v55
	v_and_b32_e32 v100, 0xffff0000, v54
	v_lshlrev_b32_e32 v15, 16, v59
	v_lshlrev_b32_e32 v14, 16, v58
	v_and_b32_e32 v19, 0xffff0000, v59
	v_and_b32_e32 v18, 0xffff0000, v58
	s_waitcnt vmcnt(16)
	v_mov_b32_e32 v54, v34
	v_mov_b32_e32 v55, v36
	v_pk_fma_f32 v[58:59], v[54:55], v[96:97], v[104:105]
	v_mov_b32_e32 v36, v35
	v_pk_fma_f32 v[104:105], v[36:37], v[94:95], v[106:107]
	s_waitcnt vmcnt(14)
	v_mov_b32_e32 v34, v38
	v_mov_b32_e32 v35, v40
	v_pk_fma_f32 v[58:59], v[34:35], v[98:99], v[58:59]
	v_mov_b32_e32 v40, v39
	s_waitcnt vmcnt(12)
; __device__ __forceinline__ unsigned pk2(float lo, float hi) { return f2bf(lo) | (f2bf(hi) << 16); }
; __device__ __forceinline__ void conv8(const bf16* proj, int t, int ch, const float* cw, const float* cb, float sc, float (&o)[8]) {
;     ...
;     for (int e = 0; e < 8; ++e) o[e] = o[e] * sc * __builtin_amdgcn_rcpf(1.0f + __expf(-o[e]));
; __device__ __forceinline__ void conv4x8(const bf16* proj, int t, int ch, const float* cw, const float* cb, float sc, float (&o)[4][8]) {
;     ...
;     for (int j = 0; j < 4; ++j)
; #pragma unroll
;         for (int e = 0; e < 8; ++e) o[j][e] = o[j][e] * sc * __builtin_amdgcn_rcpf(1.0f + __expf(-o[j][e]));
; }
; __device__ __forceinline__ u32x4 pack8(const float (&v)[8]) { u32x4 o; o.x = pk2(v[0], v[1]); o.y = pk2(v[2], v[3]); o.z = pk2(v[4], v[5]); o.w = pk2(v[6], v[7]); return o; }
; __device__ __forceinline__ void m1_phase(const Params& p, unsigned char* ldsg, int G) {
;     ...
;             for (int j = 0; j < 4; ++j) *(u32x4*)(QKC + (size_t)(t0 + l0 + j) * DM + h * HD + cgp * 8) = pack8(qv[j]);
	v_mov_b32_e32 v38, v46
	v_mov_b32_e32 v39, v48
	v_pk_fma_f32 v[58:59], v[38:39], v[14:15], v[58:59]
	v_pk_fma_f32 v[104:105], v[40:41], v[100:101], v[104:105]
	v_mul_f32_e32 v1, 0xbfb8aa3b, v58
	v_exp_f32_e32 v1, v1
	v_mov_b32_e32 v48, v47
	v_pk_fma_f32 v[46:47], v[48:49], v[18:19], v[104:105]
	v_pk_fma_f32 v[94:95], v[20:21], v[94:95], v[16:17]
	v_add_f32_e32 v1, 1.0, v1
	v_rcp_f32_e32 v104, v1
	v_mul_f32_e32 v1, 0xbfb8aa3b, v46
	v_exp_f32_e32 v1, v1
	v_pk_fma_f32 v[94:95], v[36:37], v[100:101], v[94:95]
	v_add_f32_e32 v1, 1.0, v1
	v_rcp_f32_e32 v108, v1
	v_mul_f32_e32 v1, 0xbfb8aa3b, v59
	v_exp_f32_e32 v1, v1
	v_pk_fma_f32 v[94:95], v[40:41], v[18:19], v[94:95]
	v_add_f32_e32 v1, 1.0, v1
	v_rcp_f32_e32 v105, v1
	v_mul_f32_e32 v1, 0xbfb8aa3b, v47
	v_exp_f32_e32 v1, v1
	v_pk_mul_f32 v[106:107], v[58:59], v[104:105]
	v_mov_b32_e32 v58, v6
	v_add_f32_e32 v1, 1.0, v1
	v_rcp_f32_e32 v109, v1
	v_mov_b32_e32 v59, v8
	v_and_b32_e32 v105, 0xffff0000, v57
	v_and_b32_e32 v104, 0xffff0000, v56
	v_pk_mul_f32 v[108:109], v[46:47], v[108:109]
	v_mov_b32_e32 v46, v10
	v_mov_b32_e32 v47, v12
	v_pk_fma_f32 v[114:115], v[46:47], v[102:103], v[58:59]
	v_lshlrev_b32_e32 v103, 16, v57
	v_lshlrev_b32_e32 v102, 16, v56
	v_mov_b32_e32 v56, v22
	v_mov_b32_e32 v57, v24
	v_mov_b32_e32 v12, v11
	v_mov_b32_e32 v8, v7
	v_lshlrev_b32_e32 v7, 16, v61
	v_lshlrev_b32_e32 v6, 16, v60
	v_and_b32_e32 v11, 0xffff0000, v61
	v_and_b32_e32 v10, 0xffff0000, v60
	v_pk_fma_f32 v[60:61], v[56:57], v[90:91], v[114:115]
	v_mov_b32_e32 v24, v23
	v_mov_b32_e32 v22, v26
	v_mov_b32_e32 v23, v28
	v_pk_fma_f32 v[60:61], v[22:23], v[102:103], v[60:61]
	v_mov_b32_e32 v28, v27
	s_waitcnt vmcnt(11)
	v_mov_b32_e32 v26, v42
	v_mov_b32_e32 v27, v44
	v_pk_fma_f32 v[60:61], v[26:27], v[6:7], v[60:61]
	v_pk_fma_f32 v[82:83], v[12:13], v[82:83], v[8:9]
	v_mul_f32_e32 v1, 0xbfb8aa3b, v60
	v_exp_f32_e32 v1, v1
	v_pk_fma_f32 v[82:83], v[24:25], v[84:85], v[82:83]
	v_mov_b32_e32 v44, v43
	v_pk_fma_f32 v[82:83], v[28:29], v[104:105], v[82:83]
	v_add_f32_e32 v1, 1.0, v1
	v_pk_fma_f32 v[42:43], v[44:45], v[10:11], v[82:83]
	v_rcp_f32_e32 v82, v1
	v_mul_f32_e32 v1, 0xbfb8aa3b, v42
	v_exp_f32_e32 v1, v1
	v_bfe_u32 v77, v109, 16, 1
	v_add3_u32 v77, v109, v77, s81
	v_bfe_u32 v79, v108, 16, 1
	v_add_f32_e32 v1, 1.0, v1
	v_rcp_f32_e32 v114, v1
	v_mul_f32_e32 v1, 0xbfb8aa3b, v61
	v_exp_f32_e32 v1, v1
	v_add3_u32 v79, v108, v79, s81
	v_pk_fma_f32 v[90:91], v[46:47], v[90:91], v[58:59]
	v_pk_fma_f32 v[84:85], v[12:13], v[84:85], v[8:9]
	v_add_f32_e32 v1, 1.0, v1
	v_rcp_f32_e32 v83, v1
	v_mul_f32_e32 v1, 0xbfb8aa3b, v43
	v_exp_f32_e32 v1, v1
	v_pk_fma_f32 v[90:91], v[56:57], v[102:103], v[90:91]
	v_pk_mul_f32 v[60:61], v[60:61], v[82:83]
	v_pk_fma_f32 v[90:91], v[22:23], v[6:7], v[90:91]
	v_add_f32_e32 v1, 1.0, v1
	v_rcp_f32_e32 v115, v1
	v_bfe_u32 v81, v60, 16, 1
	v_bfe_u32 v82, v61, 16, 1
	v_add3_u32 v61, v61, v82, s81
	v_pk_mul_f32 v[42:43], v[42:43], v[114:115]
	v_add3_u32 v60, v60, v81, s81
	v_bfe_u32 v75, v42, 16, 1
	v_add3_u32 v42, v42, v75, s81
	v_bfe_u32 v75, v107, 16, 1
	v_bfe_u32 v1, v43, 16, 1
	v_add3_u32 v75, v107, v75, s81
	v_add3_u32 v1, v43, v1, s81
	v_bfe_u32 v43, v106, 16, 1
	v_lshrrev_b32_e32 v75, 16, v75
	v_add3_u32 v43, v106, v43, s81
	v_and_or_b32 v107, v77, s64, v75
	v_ashrrev_i32_e32 v75, 31, v74
	v_lshrrev_b32_e32 v43, 16, v43
	v_lshrrev_b32_e32 v60, 16, v60
	v_lshrrev_b32_e32 v61, 16, v61
	v_lshlrev_b64 v[82:83], 11, v[74:75]
	v_and_or_b32 v109, v1, s64, v61
	v_and_or_b32 v108, v42, s64, v60
	v_and_or_b32 v106, v79, s64, v43
	v_lshl_add_u64 v[42:43], v[62:63], 0, v[82:83]
	global_store_dwordx4 v[42:43], v[106:109], off
	v_pk_fma_f32 v[42:43], v[86:87], v[96:97], v[88:89]
	v_lshlrev_b32_e32 v61, 16, v51
	v_pk_fma_f32 v[42:43], v[54:55], v[98:99], v[42:43]
	v_lshlrev_b32_e32 v60, 16, v50
	v_pk_fma_f32 v[42:43], v[34:35], v[14:15], v[42:43]
	v_and_b32_e32 v51, 0xffff0000, v51
	v_pk_fma_f32 v[42:43], v[38:39], v[60:61], v[42:43]
	v_and_b32_e32 v50, 0xffff0000, v50
	v_mul_f32_e32 v1, 0xbfb8aa3b, v42
	v_exp_f32_e32 v1, v1
	v_pk_fma_f32 v[94:95], v[48:49], v[50:51], v[94:95]
	v_pk_fma_f32 v[84:85], v[24:25], v[104:105], v[84:85]
	v_add_f32_e32 v1, 1.0, v1
	v_rcp_f32_e32 v96, v1
	v_mul_f32_e32 v1, 0xbfb8aa3b, v94
	v_exp_f32_e32 v1, v1
	v_pk_fma_f32 v[84:85], v[28:29], v[10:11], v[84:85]
	v_add_f32_e32 v1, 1.0, v1
	v_rcp_f32_e32 v106, v1
	v_mul_f32_e32 v1, 0xbfb8aa3b, v43
	v_exp_f32_e32 v1, v1
	s_nop 0
	v_add_f32_e32 v1, 1.0, v1
	v_rcp_f32_e32 v97, v1
	v_mul_f32_e32 v1, 0xbfb8aa3b, v95
	v_exp_f32_e32 v1, v1
	v_pk_mul_f32 v[96:97], v[42:43], v[96:97]
	v_lshlrev_b32_e32 v43, 16, v53
	v_lshlrev_b32_e32 v42, 16, v52
	v_add_f32_e32 v1, 1.0, v1
	v_pk_fma_f32 v[90:91], v[26:27], v[42:43], v[90:91]
	v_rcp_f32_e32 v107, v1
	v_mul_f32_e32 v1, 0xbfb8aa3b, v90
	v_exp_f32_e32 v1, v1
	v_and_b32_e32 v53, 0xffff0000, v53
	v_and_b32_e32 v52, 0xffff0000, v52
	v_pk_fma_f32 v[84:85], v[44:45], v[52:53], v[84:85]
	v_add_f32_e32 v1, 1.0, v1
	v_pk_mul_f32 v[94:95], v[94:95], v[106:107]
	v_rcp_f32_e32 v106, v1
	v_mul_f32_e32 v1, 0xbfb8aa3b, v84
	v_exp_f32_e32 v1, v1
	v_bfe_u32 v77, v95, 16, 1
	v_bfe_u32 v79, v94, 16, 1
	v_add3_u32 v79, v94, v79, s81
	v_add_f32_e32 v1, 1.0, v1
	v_rcp_f32_e32 v108, v1
	v_mul_f32_e32 v1, 0xbfb8aa3b, v91
	v_exp_f32_e32 v1, v1
	v_add3_u32 v77, v95, v77, s81
	v_bfe_u32 v81, v96, 16, 1
	v_add3_u32 v81, v96, v81, s81
	v_add_f32_e32 v1, 1.0, v1
	v_rcp_f32_e32 v107, v1
	v_mul_f32_e32 v1, 0xbfb8aa3b, v85
	v_exp_f32_e32 v1, v1
	v_lshrrev_b32_e32 v81, 16, v81
	v_pk_mul_f32 v[90:91], v[90:91], v[106:107]
	v_add_f32_e32 v1, 1.0, v1
	v_rcp_f32_e32 v109, v1
	v_bfe_u32 v94, v91, 16, 1
	v_add3_u32 v91, v91, v94, s81
; __device__ __forceinline__ unsigned pk2(float lo, float hi) { return f2bf(lo) | (f2bf(hi) << 16); }
; __device__ __forceinline__ void conv4x8(const bf16* proj, int t, int ch, const float* cw, const float* cb, float sc, float (&o)[4][8]) {
;     ...
;     for (int j = 0; j < 4; ++j)
; #pragma unroll
;         for (int e = 0; e < 8; ++e) o[j][e] = o[j][e] * sc * __builtin_amdgcn_rcpf(1.0f + __expf(-o[j][e]));
; }
; __device__ __forceinline__ u32x4 pack8(const float (&v)[8]) { u32x4 o; o.x = pk2(v[0], v[1]); o.y = pk2(v[2], v[3]); o.z = pk2(v[4], v[5]); o.w = pk2(v[6], v[7]); return o; }
; __device__ __forceinline__ void m1_phase(const Params& p, unsigned char* ldsg, int G) {
;     ...
;             for (int j = 0; j < 4; ++j) *(u32x4*)(QKC + (size_t)(t0 + l0 + j) * DM + h * HD + cgp * 8) = pack8(qv[j]);
	v_and_or_b32 v94, v79, s64, v81
	v_pk_mul_f32 v[84:85], v[84:85], v[108:109]
	s_nop 0
	v_bfe_u32 v75, v84, 16, 1
	v_bfe_u32 v1, v85, 16, 1
	v_add3_u32 v75, v84, v75, s81
	v_bfe_u32 v84, v97, 16, 1
	v_add3_u32 v1, v85, v1, s81
	v_bfe_u32 v85, v90, 16, 1
	v_add3_u32 v84, v97, v84, s81
	v_add3_u32 v85, v90, v85, s81
	v_lshrrev_b32_e32 v84, 16, v84
	v_lshrrev_b32_e32 v85, 16, v85
	v_and_or_b32 v95, v77, s64, v84
	v_ashrrev_i32_e32 v77, 31, v76
	v_lshrrev_b32_e32 v90, 16, v91
	v_and_or_b32 v96, v75, s64, v85
	v_lshlrev_b64 v[84:85], 11, v[76:77]
	v_and_or_b32 v97, v1, s64, v90
	v_lshl_add_u64 v[90:91], v[62:63], 0, v[84:85]
	global_store_dwordx4 v[90:91], v[94:97], off
	v_pk_fma_f32 v[90:91], v[20:21], v[100:101], v[16:17]
	v_pk_fma_f32 v[16:17], v[20:21], v[18:19], v[16:17]
	v_lshlrev_b32_e32 v95, 16, v31
	v_lshlrev_b32_e32 v94, 16, v30
	v_and_b32_e32 v97, 0xffff0000, v31
	v_and_b32_e32 v96, 0xffff0000, v30
	v_pk_fma_f32 v[30:31], v[86:87], v[98:99], v[88:89]
	v_pk_fma_f32 v[90:91], v[36:37], v[18:19], v[90:91]
	v_pk_fma_f32 v[30:31], v[54:55], v[14:15], v[30:31]
	v_pk_fma_f32 v[90:91], v[40:41], v[50:51], v[90:91]
	v_pk_fma_f32 v[30:31], v[34:35], v[60:61], v[30:31]
	v_pk_fma_f32 v[90:91], v[48:49], v[96:97], v[90:91]
	v_pk_fma_f32 v[30:31], v[38:39], v[94:95], v[30:31]
	v_pk_fma_f32 v[14:15], v[86:87], v[14:15], v[88:89]
	v_mul_f32_e32 v1, 0xbfb8aa3b, v30
	v_exp_f32_e32 v1, v1
	v_pk_fma_f32 v[14:15], v[54:55], v[60:61], v[14:15]
	v_pk_fma_f32 v[16:17], v[36:37], v[50:51], v[16:17]
	v_pk_fma_f32 v[14:15], v[34:35], v[94:95], v[14:15]
	v_add_f32_e32 v1, 1.0, v1
	v_rcp_f32_e32 v98, v1
	v_mul_f32_e32 v1, 0xbfb8aa3b, v90
	v_exp_f32_e32 v1, v1
	v_pk_fma_f32 v[16:17], v[40:41], v[96:97], v[16:17]
	v_add_f32_e32 v1, 1.0, v1
	v_rcp_f32_e32 v100, v1
	v_mul_f32_e32 v1, 0xbfb8aa3b, v31
	v_exp_f32_e32 v1, v1
	s_nop 0
	v_add_f32_e32 v1, 1.0, v1
	v_rcp_f32_e32 v99, v1
	v_mul_f32_e32 v1, 0xbfb8aa3b, v91
	v_exp_f32_e32 v1, v1
	v_pk_mul_f32 v[30:31], v[30:31], v[98:99]
	v_lshlrev_b32_e32 v99, 16, v33
	v_add_f32_e32 v1, 1.0, v1
	v_rcp_f32_e32 v101, v1
	v_lshlrev_b32_e32 v98, 16, v32
	v_bfe_u32 v81, v30, 16, 1
	v_add3_u32 v30, v30, v81, s81
	v_pk_mul_f32 v[90:91], v[90:91], v[100:101]
	v_and_b32_e32 v101, 0xffff0000, v33
	v_and_b32_e32 v100, 0xffff0000, v32
	v_pk_fma_f32 v[32:33], v[46:47], v[102:103], v[58:59]
	v_pk_fma_f32 v[102:103], v[12:13], v[104:105], v[8:9]
	v_pk_fma_f32 v[32:33], v[56:57], v[6:7], v[32:33]
	v_pk_fma_f32 v[102:103], v[24:25], v[10:11], v[102:103]
	v_pk_fma_f32 v[32:33], v[22:23], v[42:43], v[32:33]
	v_pk_fma_f32 v[102:103], v[28:29], v[52:53], v[102:103]
	v_pk_fma_f32 v[32:33], v[26:27], v[98:99], v[32:33]
	v_pk_fma_f32 v[102:103], v[44:45], v[100:101], v[102:103]
	v_mul_f32_e32 v1, 0xbfb8aa3b, v32
	v_exp_f32_e32 v1, v1
	v_bfe_u32 v77, v91, 16, 1
	v_bfe_u32 v79, v90, 16, 1
	v_add3_u32 v79, v90, v79, s81
	v_add_f32_e32 v1, 1.0, v1
	v_rcp_f32_e32 v104, v1
	v_mul_f32_e32 v1, 0xbfb8aa3b, v102
	v_exp_f32_e32 v1, v1
	v_add3_u32 v77, v91, v77, s81
	v_bfe_u32 v90, v31, 16, 1
	v_lshrrev_b32_e32 v30, 16, v30
	v_add_f32_e32 v1, 1.0, v1
	v_rcp_f32_e32 v106, v1
	v_mul_f32_e32 v1, 0xbfb8aa3b, v33
	v_exp_f32_e32 v1, v1
	v_add3_u32 v31, v31, v90, s81
	v_and_or_b32 v30, v79, s64, v30
	v_ashrrev_i32_e32 v79, 31, v78
	v_add_f32_e32 v1, 1.0, v1
	v_rcp_f32_e32 v105, v1
	v_mul_f32_e32 v1, 0xbfb8aa3b, v103
	v_exp_f32_e32 v1, v1
	v_lshrrev_b32_e32 v31, 16, v31
	v_pk_mul_f32 v[32:33], v[32:33], v[104:105]
	v_and_or_b32 v31, v77, s64, v31
	v_add_f32_e32 v1, 1.0, v1
	v_rcp_f32_e32 v107, v1
	v_bfe_u32 v91, v32, 16, 1
	v_add3_u32 v32, v32, v91, s81
	v_lshrrev_b32_e32 v32, 16, v32
	v_pk_mul_f32 v[102:103], v[102:103], v[106:107]
	v_lshlrev_b64 v[90:91], 11, v[78:79]
	v_bfe_u32 v75, v102, 16, 1
	v_add3_u32 v75, v102, v75, s81
	v_bfe_u32 v102, v33, 16, 1
	v_bfe_u32 v1, v103, 16, 1
	v_add3_u32 v33, v33, v102, s81
	v_add3_u32 v1, v103, v1, s81
	v_lshrrev_b32_e32 v33, 16, v33
	v_and_or_b32 v33, v1, s64, v33
	v_and_or_b32 v32, v75, s64, v32
	v_lshl_add_u64 v[102:103], v[62:63], 0, v[90:91]
	global_store_dwordx4 v[102:103], v[30:33], off
	v_pk_fma_f32 v[6:7], v[46:47], v[6:7], v[58:59]
	v_pk_fma_f32 v[8:9], v[12:13], v[10:11], v[8:9]
	v_lshlrev_b32_e32 v31, 16, v3
	v_lshlrev_b32_e32 v30, 16, v2
	v_pk_fma_f32 v[14:15], v[38:39], v[30:31], v[14:15]
	v_and_b32_e32 v3, 0xffff0000, v3
	v_mul_f32_e32 v1, 0xbfb8aa3b, v14
	v_exp_f32_e32 v1, v1
	v_and_b32_e32 v2, 0xffff0000, v2
	v_pk_fma_f32 v[2:3], v[48:49], v[2:3], v[16:17]
	v_pk_fma_f32 v[6:7], v[56:57], v[42:43], v[6:7]
	v_add_f32_e32 v1, 1.0, v1
	v_rcp_f32_e32 v16, v1
	v_mul_f32_e32 v1, 0xbfb8aa3b, v2
	v_exp_f32_e32 v1, v1
	v_pk_fma_f32 v[6:7], v[22:23], v[98:99], v[6:7]
	v_pk_fma_f32 v[8:9], v[24:25], v[52:53], v[8:9]
	v_ashrrev_i32_e32 v81, 31, v80
	v_add_f32_e32 v1, 1.0, v1
	v_rcp_f32_e32 v18, v1
	v_mul_f32_e32 v1, 0xbfb8aa3b, v15
	v_exp_f32_e32 v1, v1
	v_pk_fma_f32 v[8:9], v[28:29], v[100:101], v[8:9]
	v_lshlrev_b64 v[86:87], 11, v[80:81]
	v_add_f32_e32 v1, 1.0, v1
	v_rcp_f32_e32 v17, v1
	v_mul_f32_e32 v1, 0xbfb8aa3b, v3
	v_exp_f32_e32 v1, v1
	v_pk_mul_f32 v[14:15], v[14:15], v[16:17]
	v_lshlrev_b32_e32 v17, 16, v5
	v_lshlrev_b32_e32 v16, 16, v4
	v_add_f32_e32 v1, 1.0, v1
	v_pk_fma_f32 v[6:7], v[26:27], v[16:17], v[6:7]
	v_rcp_f32_e32 v19, v1
	v_mul_f32_e32 v1, 0xbfb8aa3b, v6
	v_exp_f32_e32 v1, v1
	v_and_b32_e32 v5, 0xffff0000, v5
	v_and_b32_e32 v4, 0xffff0000, v4
	v_pk_fma_f32 v[4:5], v[44:45], v[4:5], v[8:9]
	v_add_f32_e32 v1, 1.0, v1
	v_rcp_f32_e32 v8, v1
	v_mul_f32_e32 v1, 0xbfb8aa3b, v4
	v_exp_f32_e32 v1, v1
	v_pk_mul_f32 v[2:3], v[2:3], v[18:19]
	v_add_f32_e32 v1, 1.0, v1
	v_rcp_f32_e32 v10, v1
; __device__ __forceinline__ u32x4 pack8(const float (&v)[8]) { u32x4 o; o.x = pk2(v[0], v[1]); o.y = pk2(v[2], v[3]); o.z = pk2(v[4], v[5]); o.w = pk2(v[6], v[7]); return o; }
; __device__ __forceinline__ void conv4x8(const bf16* proj, int t, int ch, const float* cw, const float* cb, float sc, float (&o)[4][8]) {
;     u32x4 raw[7];
; #pragma unroll
;     for (int i = 0; i < 7; ++i) { const int tr = t - 3 + i; raw[i] = tr >= 0 ? *(const u32x4*)(proj + (size_t)tr * NPROJ + ch) : (u32x4){0u, 0u, 0u, 0u}; }
;     { const f32x4 b0 = *(const f32x4*)(cb + ch), b1 = *(const f32x4*)(cb + ch + 4);
; #pragma unroll
;       for (int j = 0; j < 4; ++j) { o[j][0] = b0[0]; o[j][1] = b0[1]; o[j][2] = b0[2]; o[j][3] = b0[3]; o[j][4] = b1[0]; o[j][5] = b1[1]; o[j][6] = b1[2]; o[j][7] = b1[3]; } }
; #pragma unroll
;     for (int w = 0; w < 4; ++w) {
;         const f32x4 w0 = *(const f32x4*)(cw + w * 1024 + ch), w1 = *(const f32x4*)(cw + w * 1024 + ch + 4);
;         const float wv[8] = {w0[0], w0[1], w0[2], w0[3], w1[0], w1[1], w1[2], w1[3]};
; #pragma unroll
; __device__ __forceinline__ void m1_phase(const Params& p, unsigned char* ldsg, int G) {
;     ...
;             for (int j = 0; j < 4; ++j) *(u32x4*)(QKC + (size_t)(t0 + l0 + j) * DM + h * HD + cgp * 8) = pack8(qv[j]);
;     ...
;         conv4x8(PROJ, t0 + l0, 512 + h * HD + cgp * 8, p.convw, p.convb, 0.08838834764831845f, kk);
	v_mul_f32_e32 v1, 0xbfb8aa3b, v7
	v_exp_f32_e32 v1, v1
	s_nop 0
	v_add_f32_e32 v1, 1.0, v1
	v_rcp_f32_e32 v9, v1
	v_mul_f32_e32 v1, 0xbfb8aa3b, v5
	v_exp_f32_e32 v1, v1
	v_pk_mul_f32 v[6:7], v[6:7], v[8:9]
	v_bfe_u32 v9, v3, 16, 1
	v_add_f32_e32 v1, 1.0, v1
	v_rcp_f32_e32 v11, v1
	v_add3_u32 v3, v3, v9, s81
	v_bfe_u32 v9, v6, 16, 1
	v_add3_u32 v6, v6, v9, s81
	v_pk_mul_f32 v[4:5], v[4:5], v[10:11]
	v_bfe_u32 v10, v2, 16, 1
	v_bfe_u32 v1, v5, 16, 1
	v_bfe_u32 v8, v4, 16, 1
	v_add3_u32 v2, v2, v10, s81
	v_add3_u32 v4, v4, v8, s81
	v_add3_u32 v1, v5, v1, s81
	v_bfe_u32 v5, v14, 16, 1
	v_bfe_u32 v8, v15, 16, 1
	v_bfe_u32 v10, v7, 16, 1
	v_add3_u32 v7, v7, v10, s81
	v_add3_u32 v8, v15, v8, s81
	v_add3_u32 v5, v14, v5, s81
	v_lshrrev_b32_e32 v9, 16, v5
	v_lshrrev_b32_e32 v8, 16, v8
	v_lshrrev_b32_e32 v6, 16, v6
	v_lshrrev_b32_e32 v5, 16, v7
	v_and_or_b32 v5, v1, s64, v5
	v_and_or_b32 v4, v4, s64, v6
	v_and_or_b32 v3, v3, s64, v8
	v_and_or_b32 v2, v2, s64, v9
	v_lshl_add_u64 v[6:7], v[62:63], 0, v[86:87]
	global_store_dwordx4 v[6:7], v[2:5], off
	v_add_u32_e32 v8, s58, v119
	v_ashrrev_i32_e32 v9, 31, v8
	v_lshlrev_b64 v[12:13], 2, v[8:9]
	v_lshl_add_u64 v[32:33], s[48:49], 0, v[12:13]
	v_add_co_u32_e32 v28, vcc, s65, v32
	v_lshl_add_u64 v[12:13], s[50:51], 0, v[12:13]
	s_nop 0
	v_addc_co_u32_e32 v29, vcc, 0, v33, vcc
	global_load_dwordx4 v[16:19], v[32:33], off
	global_load_dwordx4 v[8:11], v[32:33], off offset:16
	global_load_dwordx4 v[20:23], v[12:13], off
	s_nop 0
	global_load_dwordx4 v[12:15], v[12:13], off offset:16
	s_nop 0
	global_load_dwordx4 v[36:39], v[28:29], off offset:-4096
	global_load_dwordx4 v[40:43], v[28:29], off
	v_add_co_u32_e32 v28, vcc, s80, v32
	s_waitcnt vmcnt(6)
	v_lshlrev_b32_e32 v95, 16, v189
	v_addc_co_u32_e32 v29, vcc, 0, v33, vcc
	global_load_dwordx4 v[44:47], v[28:29], off
	v_lshlrev_b32_e32 v94, 16, v188
	v_and_b32_e32 v97, 0xffff0000, v189
	v_and_b32_e32 v96, 0xffff0000, v188
	v_lshl_add_u64 v[0:1], v[32:33], 0, s[6:7]
	global_load_dwordx4 v[28:31], v[0:1], off offset:16
	v_lshl_add_u64 v[0:1], v[32:33], 0, s[38:39]
	v_lshlrev_b32_e32 v101, 16, v191
	v_lshlrev_b32_e32 v100, 16, v190
	v_and_b32_e32 v107, 0xffff0000, v191
	v_and_b32_e32 v106, 0xffff0000, v190
	global_load_dwordx4 v[0:3], v[0:1], off offset:16
	v_lshl_add_u64 v[32:33], v[32:33], 0, s[40:41]
	global_load_dwordx4 v[32:35], v[32:33], off offset:16
	v_lshlrev_b32_e32 v117, 16, v193
	v_lshlrev_b32_e32 v116, 16, v192
	v_and_b32_e32 v177, 0xffff0000, v193
	v_and_b32_e32 v176, 0xffff0000, v192
	v_lshlrev_b32_e32 v113, 16, v195
	v_lshlrev_b32_e32 v112, 16, v194
	v_and_b32_e32 v115, 0xffff0000, v195
	v_and_b32_e32 v114, 0xffff0000, v194
	v_lshlrev_b32_e32 v110, 16, v196
	v_and_b32_e32 v108, 0xffff0000, v196
	v_lshlrev_b32_e32 v111, 16, v197
	v_and_b32_e32 v109, 0xffff0000, v197
	v_lshlrev_b32_e32 v104, 16, v198
	v_and_b32_e32 v102, 0xffff0000, v198
	v_lshlrev_b32_e32 v105, 16, v199
	v_and_b32_e32 v103, 0xffff0000, v199
	v_lshlrev_b32_e32 v57, 16, v201
	v_lshlrev_b32_e32 v56, 16, v200
	v_and_b32_e32 v59, 0xffff0000, v201
	v_and_b32_e32 v58, 0xffff0000, v200
	s_lshl_b64 s[0:1], s[58:59], 1
	v_lshl_add_u64 v[84:85], s[56:57], 0, v[84:85]
	v_lshl_add_u64 v[84:85], v[84:85], 0, s[0:1]
	v_lshl_add_u64 v[84:85], v[84:85], 0, v[66:67]
	v_lshl_add_u64 v[90:91], s[56:57], 0, v[90:91]
	v_lshl_add_u64 v[90:91], v[90:91], 0, s[0:1]
	v_lshl_add_u64 v[90:91], v[90:91], 0, v[66:67]
	s_waitcnt vmcnt(9)
	v_mov_b32_e32 v60, v16
	v_mov_b32_e32 v61, v18
	v_mov_b32_e32 v18, v17
	s_waitcnt vmcnt(7)
	v_mov_b32_e32 v62, v20
	v_mov_b32_e32 v63, v22
	v_mov_b32_e32 v22, v21
	v_mov_b32_e32 v52, v8
	v_mov_b32_e32 v53, v10
	v_mov_b32_e32 v10, v9
	v_pk_fma_f32 v[8:9], v[60:61], v[94:95], v[62:63]
	v_pk_fma_f32 v[16:17], v[18:19], v[96:97], v[22:23]
	s_waitcnt vmcnt(5)
	v_mov_b32_e32 v94, v36
	v_mov_b32_e32 v95, v38
	v_mov_b32_e32 v38, v37
	s_waitcnt vmcnt(4)
	v_mov_b32_e32 v96, v40
	v_mov_b32_e32 v97, v42
	v_mov_b32_e32 v42, v41
	v_pk_fma_f32 v[8:9], v[94:95], v[116:117], v[8:9]
	v_pk_fma_f32 v[16:17], v[38:39], v[176:177], v[16:17]
	s_waitcnt vmcnt(3)
	v_mov_b32_e32 v98, v44
	v_mov_b32_e32 v99, v46
	v_mov_b32_e32 v46, v45
	v_pk_fma_f32 v[8:9], v[96:97], v[110:111], v[8:9]
	v_pk_fma_f32 v[16:17], v[42:43], v[108:109], v[16:17]
	v_pk_fma_f32 v[8:9], v[98:99], v[56:57], v[8:9]
	v_pk_fma_f32 v[16:17], v[46:47], v[58:59], v[16:17]
	v_mov_b32_e32 v88, v12
	v_mul_f32_e32 v12, 0xbfb8aa3b, v8
	v_mul_f32_e32 v36, 0xbfb8aa3b, v16
	v_mul_f32_e32 v37, 0xbfb8aa3b, v9
	v_pk_mul_f32 v[20:21], v[8:9], s[42:43] op_sel_hi:[1,0]
	v_pk_mul_f32 v[8:9], v[16:17], s[42:43] op_sel_hi:[1,0]
	v_mul_f32_e32 v16, 0xbfb8aa3b, v17
	v_exp_f32_e32 v12, v12
	v_exp_f32_e32 v17, v36
	v_exp_f32_e32 v36, v37
	v_exp_f32_e32 v37, v16
	v_add_f32_e32 v12, 1.0, v12
	v_add_f32_e32 v40, 1.0, v17
	v_add_f32_e32 v17, 1.0, v36
	v_rcp_f32_e32 v16, v12
	v_rcp_f32_e32 v17, v17
	v_mov_b32_e32 v89, v14
	v_add_f32_e32 v12, 1.0, v37
	v_rcp_f32_e32 v36, v40
	v_pk_mul_f32 v[16:17], v[20:21], v[16:17]
	v_pk_fma_f32 v[20:21], v[52:53], v[100:101], v[88:89]
	v_mov_b32_e32 v14, v13
	v_lshlrev_b32_e32 v41, 16, v203
	v_lshlrev_b32_e32 v40, 16, v202
	v_and_b32_e32 v45, 0xffff0000, v203
	v_and_b32_e32 v44, 0xffff0000, v202
	s_waitcnt vmcnt(2)
	v_mov_b32_e32 v54, v28
	v_mov_b32_e32 v55, v30
	v_rcp_f32_e32 v37, v12
	v_pk_fma_f32 v[12:13], v[10:11], v[106:107], v[14:15]
	v_pk_fma_f32 v[20:21], v[54:55], v[112:113], v[20:21]
	v_mov_b32_e32 v30, v29
	s_waitcnt vmcnt(1)
	v_mov_b32_e32 v100, v0
	v_mov_b32_e32 v101, v2
	v_pk_fma_f32 v[12:13], v[30:31], v[114:115], v[12:13]
	v_pk_fma_f32 v[20:21], v[100:101], v[104:105], v[20:21]
	v_mov_b32_e32 v2, v1
	s_waitcnt vmcnt(0)
; __device__ __forceinline__ u32x4 pack8(const float (&v)[8]) { u32x4 o; o.x = pk2(v[0], v[1]); o.y = pk2(v[2], v[3]); o.z = pk2(v[4], v[5]); o.w = pk2(v[6], v[7]); return o; }
; __device__ __forceinline__ void conv4x8(const bf16* proj, int t, int ch, const float* cw, const float* cb, float sc, float (&o)[4][8]) {
;     ...
;         for (int j = 0; j < 4; ++j) { float xv[8]; unpack8(raw[j + w], xv);
; #pragma unroll
;             for (int e = 0; e < 8; ++e) o[j][e] += wv[e] * xv[e]; }
;     }
; #pragma unroll
;     for (int j = 0; j < 4; ++j)
; #pragma unroll
;         for (int e = 0; e < 8; ++e) o[j][e] = o[j][e] * sc * __builtin_amdgcn_rcpf(1.0f + __expf(-o[j][e]));
; __device__ __forceinline__ void m1_phase(const Params& p, unsigned char* ldsg, int G) {
;     ...
;         for (int j = 0; j < 4; ++j) *(u32x4*)(QKC + (size_t)(t0 + l0 + j) * DM + 512 + h * HD + cgp * 8) = pack8(kk[j]);
	v_mov_b32_e32 v106, v32
	v_mov_b32_e32 v107, v34
	v_pk_fma_f32 v[0:1], v[2:3], v[102:103], v[12:13]
	v_pk_fma_f32 v[20:21], v[106:107], v[40:41], v[20:21]
	v_mov_b32_e32 v34, v33
	v_pk_fma_f32 v[0:1], v[34:35], v[44:45], v[0:1]
	v_mul_f32_e32 v12, 0xbfb8aa3b, v20
	v_exp_f32_e32 v28, v12
	v_mul_f32_e32 v12, 0xbfb8aa3b, v0
	v_exp_f32_e32 v29, v12
	v_pk_mul_f32 v[12:13], v[8:9], v[36:37]
	v_add_f32_e32 v8, 1.0, v28
	v_mul_f32_e32 v28, 0xbfb8aa3b, v21
	v_add_f32_e32 v9, 1.0, v29
	v_exp_f32_e32 v29, v28
	v_mul_f32_e32 v28, 0xbfb8aa3b, v1
	v_exp_f32_e32 v32, v28
	v_rcp_f32_e32 v28, v9
	v_add_f32_e32 v9, 1.0, v29
	v_rcp_f32_e32 v8, v8
	v_rcp_f32_e32 v9, v9
	v_add_f32_e32 v29, 1.0, v32
	v_rcp_f32_e32 v29, v29
	v_pk_mul_f32 v[20:21], v[20:21], s[42:43] op_sel_hi:[1,0]
	v_pk_mul_f32 v[0:1], v[0:1], s[42:43] op_sel_hi:[1,0]
	v_pk_mul_f32 v[8:9], v[20:21], v[8:9]
	v_pk_mul_f32 v[0:1], v[0:1], v[28:29]
	v_bfe_u32 v36, v8, 16, 1
	v_bfe_u32 v37, v9, 16, 1
	v_bfe_u32 v20, v1, 16, 1
	v_bfe_u32 v21, v0, 16, 1
	v_add3_u32 v37, v9, v37, s81
	v_add3_u32 v36, v8, v36, s81
	v_add3_u32 v21, v0, v21, s81
	v_add3_u32 v20, v1, v20, s81
	v_bfe_u32 v32, v16, 16, 1
	v_bfe_u32 v33, v17, 16, 1
	v_lshrrev_b32_e32 v36, 16, v36
	v_lshrrev_b32_e32 v37, 16, v37
	v_bfe_u32 v28, v13, 16, 1
	v_bfe_u32 v29, v12, 16, 1
	v_add3_u32 v33, v17, v33, s81
	v_add3_u32 v32, v16, v32, s81
	v_and_or_b32 v151, v20, s64, v37
	v_and_or_b32 v150, v21, s64, v36
	v_lshl_add_u64 v[20:21], s[56:57], 0, v[82:83]
	v_add3_u32 v29, v12, v29, s81
	v_add3_u32 v28, v13, v28, s81
	v_lshrrev_b32_e32 v32, 16, v32
	v_lshrrev_b32_e32 v33, 16, v33
	v_lshl_add_u64 v[20:21], v[20:21], 0, s[0:1]
	v_and_or_b32 v149, v28, s64, v33
	v_and_or_b32 v148, v29, s64, v32
	v_lshl_add_u64 v[20:21], v[20:21], 0, v[66:67]
	v_pk_fma_f32 v[28:29], v[18:19], v[176:177], v[22:23]
	global_store_dwordx4 v[20:21], v[148:151], off offset:1024
	v_pk_fma_f32 v[20:21], v[60:61], v[116:117], v[62:63]
	v_pk_fma_f32 v[28:29], v[38:39], v[108:109], v[28:29]
	v_and_b32_e32 v83, 0xffff0000, v205
	v_and_b32_e32 v82, 0xffff0000, v204
	v_pk_fma_f32 v[20:21], v[94:95], v[110:111], v[20:21]
	v_pk_fma_f32 v[28:29], v[42:43], v[58:59], v[28:29]
	v_lshlrev_b32_e32 v117, 16, v205
	v_lshlrev_b32_e32 v116, 16, v204
	v_pk_fma_f32 v[20:21], v[96:97], v[56:57], v[20:21]
	v_pk_fma_f32 v[28:29], v[46:47], v[82:83], v[28:29]
	v_pk_fma_f32 v[20:21], v[98:99], v[116:117], v[20:21]
	v_mul_f32_e32 v33, 0xbfb8aa3b, v28
	v_mul_f32_e32 v32, 0xbfb8aa3b, v20
	v_exp_f32_e32 v33, v33
	v_mul_f32_e32 v36, 0xbfb8aa3b, v21
	v_exp_f32_e32 v32, v32
	v_exp_f32_e32 v37, v36
	v_add_f32_e32 v33, 1.0, v33
	v_rcp_f32_e32 v36, v33
	v_add_f32_e32 v32, 1.0, v32
	v_add_f32_e32 v33, 1.0, v37
	v_mul_f32_e32 v37, 0xbfb8aa3b, v29
	v_rcp_f32_e32 v32, v32
	v_rcp_f32_e32 v33, v33
	v_exp_f32_e32 v37, v37
	v_pk_mul_f32 v[20:21], v[20:21], s[42:43] op_sel_hi:[1,0]
	v_pk_fma_f32 v[48:49], v[10:11], v[114:115], v[14:15]
	v_pk_mul_f32 v[32:33], v[20:21], v[32:33]
	v_pk_mul_f32 v[20:21], v[28:29], s[42:43] op_sel_hi:[1,0]
	v_add_f32_e32 v28, 1.0, v37
	v_rcp_f32_e32 v37, v28
	v_pk_fma_f32 v[28:29], v[52:53], v[112:113], v[88:89]
	v_lshlrev_b32_e32 v113, 16, v207
	v_pk_fma_f32 v[28:29], v[54:55], v[104:105], v[28:29]
	v_lshlrev_b32_e32 v112, 16, v206
	v_pk_fma_f32 v[48:49], v[30:31], v[102:103], v[48:49]
	v_pk_fma_f32 v[28:29], v[100:101], v[40:41], v[28:29]
	v_and_b32_e32 v115, 0xffff0000, v207
	v_and_b32_e32 v114, 0xffff0000, v206
	v_pk_fma_f32 v[48:49], v[2:3], v[44:45], v[48:49]
	v_pk_fma_f32 v[28:29], v[106:107], v[112:113], v[28:29]
	v_pk_fma_f32 v[48:49], v[34:35], v[114:115], v[48:49]
	v_mul_f32_e32 v50, 0xbfb8aa3b, v28
	v_exp_f32_e32 v50, v50
	v_mul_f32_e32 v51, 0xbfb8aa3b, v48
	v_exp_f32_e32 v51, v51
	v_pk_mul_f32 v[36:37], v[20:21], v[36:37]
	v_add_f32_e32 v20, 1.0, v50
	v_mul_f32_e32 v50, 0xbfb8aa3b, v29
	v_add_f32_e32 v21, 1.0, v51
	v_exp_f32_e32 v51, v50
	v_mul_f32_e32 v50, 0xbfb8aa3b, v49
	v_exp_f32_e32 v75, v50
	v_rcp_f32_e32 v50, v21
	v_add_f32_e32 v21, 1.0, v51
	v_rcp_f32_e32 v20, v20
	v_rcp_f32_e32 v21, v21
	v_add_f32_e32 v51, 1.0, v75
	v_rcp_f32_e32 v51, v51
	v_pk_mul_f32 v[28:29], v[28:29], s[42:43] op_sel_hi:[1,0]
	v_and_b32_e32 v149, 0xffff0000, v209
	v_pk_mul_f32 v[28:29], v[28:29], v[20:21]
	v_pk_mul_f32 v[20:21], v[48:49], s[42:43] op_sel_hi:[1,0]
	v_bfe_u32 v79, v28, 16, 1
	v_pk_mul_f32 v[20:21], v[20:21], v[50:51]
	v_bfe_u32 v50, v37, 16, 1
	v_bfe_u32 v51, v36, 16, 1
	v_add3_u32 v75, v36, v51, s81
	v_add3_u32 v77, v37, v50, s81
	v_bfe_u32 v50, v32, 16, 1
	v_bfe_u32 v51, v33, 16, 1
	v_bfe_u32 v81, v29, 16, 1
	v_bfe_u32 v48, v21, 16, 1
	v_bfe_u32 v49, v20, 16, 1
	v_add3_u32 v81, v29, v81, s81
	v_add3_u32 v79, v28, v79, s81
	v_add3_u32 v51, v33, v51, s81
	v_add3_u32 v50, v32, v50, s81
	v_add3_u32 v49, v20, v49, s81
	v_add3_u32 v48, v21, v48, s81
	v_lshrrev_b32_e32 v147, 16, v50
	v_lshrrev_b32_e32 v148, 16, v51
	v_lshrrev_b32_e32 v50, 16, v79
	v_lshrrev_b32_e32 v51, 16, v81
	v_and_or_b32 v51, v48, s64, v51
	v_and_or_b32 v50, v49, s64, v50
	v_and_or_b32 v49, v77, s64, v148
	v_and_or_b32 v48, v75, s64, v147
	global_store_dwordx4 v[84:85], v[48:51], off offset:1024
	v_lshlrev_b32_e32 v85, 16, v209
	v_lshlrev_b32_e32 v84, 16, v208
	v_and_b32_e32 v148, 0xffff0000, v208
	v_pk_fma_f32 v[24:25], v[60:61], v[110:111], v[62:63]
	v_pk_fma_f32 v[48:49], v[18:19], v[108:109], v[22:23]
	v_pk_fma_f32 v[24:25], v[94:95], v[56:57], v[24:25]
	v_pk_fma_f32 v[48:49], v[38:39], v[58:59], v[48:49]
	v_pk_fma_f32 v[24:25], v[96:97], v[116:117], v[24:25]
	v_pk_fma_f32 v[48:49], v[42:43], v[82:83], v[48:49]
	v_pk_fma_f32 v[24:25], v[98:99], v[84:85], v[24:25]
	v_lshlrev_b32_e32 v111, 16, v211
; __device__ __forceinline__ u32x4 pack8(const float (&v)[8]) { u32x4 o; o.x = pk2(v[0], v[1]); o.y = pk2(v[2], v[3]); o.z = pk2(v[4], v[5]); o.w = pk2(v[6], v[7]); return o; }
; __device__ __forceinline__ void conv4x8(const bf16* proj, int t, int ch, const float* cw, const float* cb, float sc, float (&o)[4][8]) {
;     ...
;         for (int j = 0; j < 4; ++j) { float xv[8]; unpack8(raw[j + w], xv);
; #pragma unroll
;             for (int e = 0; e < 8; ++e) o[j][e] += wv[e] * xv[e]; }
;     }
; #pragma unroll
;     for (int j = 0; j < 4; ++j)
; #pragma unroll
;         for (int e = 0; e < 8; ++e) o[j][e] = o[j][e] * sc * __builtin_amdgcn_rcpf(1.0f + __expf(-o[j][e]));
; __device__ __forceinline__ void m1_phase(const Params& p, unsigned char* ldsg, int G) {
;     ...
;         for (int j = 0; j < 4; ++j) *(u32x4*)(QKC + (size_t)(t0 + l0 + j) * DM + 512 + h * HD + cgp * 8) = pack8(kk[j]);
	v_mul_f32_e32 v50, 0xbfb8aa3b, v24
	v_exp_f32_e32 v75, v50
	v_pk_fma_f32 v[50:51], v[46:47], v[148:149], v[48:49]
	v_lshlrev_b32_e32 v110, 16, v210
	v_mul_f32_e32 v49, 0xbfb8aa3b, v50
	v_add_f32_e32 v48, 1.0, v75
	v_exp_f32_e32 v49, v49
	v_mul_f32_e32 v75, 0xbfb8aa3b, v25
	v_exp_f32_e32 v75, v75
	v_rcp_f32_e32 v48, v48
	v_add_f32_e32 v49, 1.0, v49
	v_rcp_f32_e32 v108, v49
	v_add_f32_e32 v49, 1.0, v75
	v_mul_f32_e32 v75, 0xbfb8aa3b, v51
	v_rcp_f32_e32 v49, v49
	v_exp_f32_e32 v75, v75
	v_pk_mul_f32 v[24:25], v[24:25], s[42:43] op_sel_hi:[1,0]
	v_and_b32_e32 v151, 0xffff0000, v211
	v_pk_mul_f32 v[48:49], v[24:25], v[48:49]
	v_pk_mul_f32 v[24:25], v[50:51], s[42:43] op_sel_hi:[1,0]
	v_add_f32_e32 v50, 1.0, v75
	v_and_b32_e32 v150, 0xffff0000, v210
	v_pk_fma_f32 v[26:27], v[52:53], v[104:105], v[88:89]
	v_rcp_f32_e32 v109, v50
	v_pk_fma_f32 v[50:51], v[10:11], v[102:103], v[14:15]
	v_pk_fma_f32 v[26:27], v[54:55], v[40:41], v[26:27]
	v_pk_fma_f32 v[50:51], v[30:31], v[44:45], v[50:51]
	v_pk_fma_f32 v[26:27], v[100:101], v[112:113], v[26:27]
	v_pk_fma_f32 v[50:51], v[2:3], v[114:115], v[50:51]
	v_pk_fma_f32 v[26:27], v[106:107], v[110:111], v[26:27]
	v_pk_fma_f32 v[102:103], v[34:35], v[150:151], v[50:51]
	v_mul_f32_e32 v50, 0xbfb8aa3b, v26
	v_exp_f32_e32 v75, v50
	v_mul_f32_e32 v50, 0xbfb8aa3b, v102
	v_exp_f32_e32 v77, v50
	v_pk_mul_f32 v[50:51], v[24:25], v[108:109]
	v_add_f32_e32 v24, 1.0, v75
	v_mul_f32_e32 v75, 0xbfb8aa3b, v27
	v_add_f32_e32 v25, 1.0, v77
	v_exp_f32_e32 v75, v75
	v_mul_f32_e32 v77, 0xbfb8aa3b, v103
	v_exp_f32_e32 v77, v77
	v_rcp_f32_e32 v104, v25
	v_add_f32_e32 v25, 1.0, v75
	v_rcp_f32_e32 v24, v24
	v_rcp_f32_e32 v25, v25
	v_add_f32_e32 v75, 1.0, v77
	v_rcp_f32_e32 v105, v75
	v_pk_mul_f32 v[26:27], v[26:27], s[42:43] op_sel_hi:[1,0]
	v_bfe_u32 v79, v51, 16, 1
	v_pk_mul_f32 v[26:27], v[26:27], v[24:25]
	v_pk_mul_f32 v[24:25], v[102:103], s[42:43] op_sel_hi:[1,0]
	v_bfe_u32 v102, v48, 16, 1
	v_pk_mul_f32 v[24:25], v[24:25], v[104:105]
	v_bfe_u32 v103, v49, 16, 1
	v_bfe_u32 v104, v26, 16, 1
	v_bfe_u32 v105, v27, 16, 1
	v_bfe_u32 v75, v25, 16, 1
	v_bfe_u32 v77, v24, 16, 1
	v_bfe_u32 v81, v50, 16, 1
	v_add3_u32 v105, v27, v105, s81
	v_add3_u32 v104, v26, v104, s81
	v_add3_u32 v103, v49, v103, s81
	v_add3_u32 v102, v48, v102, s81
	v_add3_u32 v81, v50, v81, s81
	v_add3_u32 v79, v51, v79, s81
	v_add3_u32 v77, v24, v77, s81
	v_add3_u32 v75, v25, v75, s81
	v_lshrrev_b32_e32 v102, 16, v102
	v_lshrrev_b32_e32 v103, 16, v103
	v_lshrrev_b32_e32 v104, 16, v104
	v_lshrrev_b32_e32 v105, 16, v105
	v_pk_fma_f32 v[18:19], v[18:19], v[58:59], v[22:23]
	v_and_or_b32 v105, v75, s64, v105
	v_and_or_b32 v104, v77, s64, v104
	v_and_or_b32 v103, v79, s64, v103
	v_and_or_b32 v102, v81, s64, v102
	v_pk_fma_f32 v[56:57], v[60:61], v[56:57], v[62:63]
	v_pk_fma_f32 v[18:19], v[38:39], v[82:83], v[18:19]
	global_store_dwordx4 v[90:91], v[102:105], off offset:1024
	v_lshlrev_b32_e32 v91, 16, v213
	v_lshlrev_b32_e32 v90, 16, v212
	v_and_b32_e32 v5, 0xffff0000, v213
	v_and_b32_e32 v4, 0xffff0000, v212
	v_pk_fma_f32 v[22:23], v[94:95], v[116:117], v[56:57]
	v_pk_fma_f32 v[18:19], v[42:43], v[148:149], v[18:19]
	v_pk_fma_f32 v[22:23], v[96:97], v[84:85], v[22:23]
	v_pk_fma_f32 v[4:5], v[46:47], v[4:5], v[18:19]
	v_pk_fma_f32 v[22:23], v[98:99], v[90:91], v[22:23]
	v_mul_f32_e32 v19, 0xbfb8aa3b, v4
	v_mul_f32_e32 v56, 0xbfb8aa3b, v22
	v_exp_f32_e32 v19, v19
	v_mul_f32_e32 v38, 0xbfb8aa3b, v23
	v_exp_f32_e32 v56, v56
	v_exp_f32_e32 v39, v38
	v_add_f32_e32 v19, 1.0, v19
	v_rcp_f32_e32 v38, v19
	v_add_f32_e32 v18, 1.0, v56
	v_add_f32_e32 v19, 1.0, v39
	v_mul_f32_e32 v39, 0xbfb8aa3b, v5
	v_rcp_f32_e32 v18, v18
	v_rcp_f32_e32 v19, v19
	v_exp_f32_e32 v39, v39
	v_pk_mul_f32 v[22:23], v[22:23], s[42:43] op_sel_hi:[1,0]
	v_pk_fma_f32 v[40:41], v[52:53], v[40:41], v[88:89]
	v_pk_mul_f32 v[18:19], v[22:23], v[18:19]
	v_add_f32_e32 v22, 1.0, v39
	v_pk_fma_f32 v[10:11], v[10:11], v[44:45], v[14:15]
	v_pk_fma_f32 v[14:15], v[54:55], v[112:113], v[40:41]
	v_rcp_f32_e32 v39, v22
	v_lshlrev_b32_e32 v23, 16, v215
	v_lshlrev_b32_e32 v22, 16, v214
	v_pk_fma_f32 v[10:11], v[30:31], v[114:115], v[10:11]
	v_pk_fma_f32 v[14:15], v[100:101], v[110:111], v[14:15]
	v_and_b32_e32 v7, 0xffff0000, v215
	v_and_b32_e32 v6, 0xffff0000, v214
	v_pk_fma_f32 v[2:3], v[2:3], v[150:151], v[10:11]
	v_pk_fma_f32 v[10:11], v[106:107], v[22:23], v[14:15]
	v_pk_fma_f32 v[2:3], v[34:35], v[6:7], v[2:3]
	v_mul_f32_e32 v6, 0xbfb8aa3b, v10
	v_exp_f32_e32 v6, v6
	v_mul_f32_e32 v7, 0xbfb8aa3b, v2
	v_exp_f32_e32 v7, v7
	v_pk_mul_f32 v[4:5], v[4:5], s[42:43] op_sel_hi:[1,0]
	s_nop 0
	v_pk_mul_f32 v[14:15], v[4:5], v[38:39]
	v_add_f32_e32 v4, 1.0, v6
	v_mul_f32_e32 v6, 0xbfb8aa3b, v11
	v_add_f32_e32 v5, 1.0, v7
	v_exp_f32_e32 v7, v6
	v_mul_f32_e32 v6, 0xbfb8aa3b, v3
	v_exp_f32_e32 v22, v6
	v_rcp_f32_e32 v6, v5
	v_add_f32_e32 v5, 1.0, v7
	v_rcp_f32_e32 v4, v4
	v_add_f32_e32 v7, 1.0, v22
	v_rcp_f32_e32 v5, v5
	v_rcp_f32_e32 v7, v7
	v_pk_mul_f32 v[10:11], v[10:11], s[42:43] op_sel_hi:[1,0]
	v_pk_mul_f32 v[2:3], v[2:3], s[42:43] op_sel_hi:[1,0]
	v_pk_mul_f32 v[10:11], v[10:11], v[4:5]
	v_pk_mul_f32 v[2:3], v[2:3], v[6:7]
	v_bfe_u32 v6, v15, 16, 1
	v_bfe_u32 v7, v14, 16, 1
	v_add3_u32 v22, v14, v7, s81
	v_add3_u32 v23, v15, v6, s81
	v_bfe_u32 v6, v18, 16, 1
	v_bfe_u32 v7, v19, 16, 1
	v_bfe_u32 v30, v10, 16, 1
	v_bfe_u32 v31, v11, 16, 1
	v_bfe_u32 v4, v3, 16, 1
	v_bfe_u32 v5, v2, 16, 1
	v_add3_u32 v31, v11, v31, s81
	v_add3_u32 v30, v10, v30, s81
	v_add3_u32 v7, v19, v7, s81
	v_add3_u32 v6, v18, v6, s81
	v_add3_u32 v5, v2, v5, s81
	v_add3_u32 v4, v3, v4, s81
	v_lshrrev_b32_e32 v34, 16, v6
	v_lshrrev_b32_e32 v35, 16, v7
; __device__ __forceinline__ unsigned pk2(float lo, float hi) { return f2bf(lo) | (f2bf(hi) << 16); }
; __device__ __forceinline__ u32x4 pack8(const float (&v)[8]) { u32x4 o; o.x = pk2(v[0], v[1]); o.y = pk2(v[2], v[3]); o.z = pk2(v[4], v[5]); o.w = pk2(v[6], v[7]); return o; }
; __device__ __forceinline__ void m1_phase(const Params& p, unsigned char* ldsg, int G) {
;     ...
;         for (int j = 0; j < 4; ++j) *(u32x4*)(QKC + (size_t)(t0 + l0 + j) * DM + 512 + h * HD + cgp * 8) = pack8(kk[j]);
;         {
;             u32x4 rv[4];
; #pragma unroll
;             for (int j = 0; j < 4; ++j) rv[j] = *(const u32x4*)(PROJ + (size_t)(t0 + l0 + j) * NPROJ + 1024 + h * HD + cgp * 8);
; #pragma unroll
;             for (int e = 0; e < 8; ++e) {
;                 const unsigned sh = (e & 1) * 16;
;                 u32x2 o; o.x = ((rv[0][e >> 1] >> sh) & 0xffffu) | (((rv[1][e >> 1] >> sh) & 0xffffu) << 16); o.y = ((rv[2][e >> 1] >> sh) & 0xffffu) | (((rv[3][e >> 1] >> sh) & 0xffffu) << 16);
;                 *(u32x2*)(VT + tsw(cgp * 8 + e, l0)) = o;
;             }
;         }
;         __syncthreads();
;         {
;             const f32x4 w4 = *(const f32x4*)(sW + l0);
; #pragma unroll
;             for (int e = 0; e < 8; ++e) { u32x2 o; o.x = pk2(kk[0][e] * w4[0], kk[1][e] * w4[1]); o.y = pk2(kk[2][e] * w4[2], kk[3][e] * w4[3]); *(u32x2*)(KT + tsw(cgp * 8 + e, l0)) = o; }
	v_lshrrev_b32_e32 v6, 16, v30
	v_lshrrev_b32_e32 v7, 16, v31
	v_and_or_b32 v7, v4, s64, v7
	v_and_or_b32 v6, v5, s64, v6
	v_and_or_b32 v5, v23, s64, v35
	v_and_or_b32 v4, v22, s64, v34
	v_lshl_add_u64 v[22:23], s[56:57], 0, v[86:87]
	v_lshl_add_u64 v[22:23], v[22:23], 0, s[0:1]
	v_lshl_add_u64 v[22:23], v[22:23], 0, v[66:67]
	global_store_dwordx4 v[22:23], v[4:7], off offset:1024
	v_add_u32_e32 v34, 0x4800, v142
	v_mov_b32_e32 v35, v18
	s_lshl_b32 s0, s44, 14
	s_add_i32 s0, s0, s83
	v_and_b32_e32 v22, 0xffff, v216
	v_lshrrev_b32_e32 v4, 16, v216
	v_and_or_b32 v30, v220, s64, v4
	v_lshl_or_b32 v22, v220, 16, v22
	v_add_u32_e32 v38, s0, v127
	v_and_b32_e32 v23, 0xffff, v224
	v_lshrrev_b32_e32 v4, 16, v224
	v_lshl_or_b32 v23, v250, 16, v23
	v_and_or_b32 v31, v250, s64, v4
	v_and_b32_e32 v4, 0xffff, v217
	ds_write2_b64 v34, v[22:23], v[30:31] offset1:18
	v_lshl_or_b32 v22, v221, 16, v4
	v_and_b32_e32 v4, 0xffff, v225
	v_lshl_or_b32 v23, v251, 16, v4
	v_lshrrev_b32_e32 v4, 16, v217
	v_lshrrev_b32_e32 v5, 16, v225
	v_and_or_b32 v4, v221, s64, v4
	v_and_or_b32 v5, v251, s64, v5
	ds_write2_b64 v34, v[22:23], v[4:5] offset0:36 offset1:54
	v_and_b32_e32 v4, 0xffff, v218
	v_lshrrev_b32_e32 v6, 16, v218
	v_and_b32_e32 v5, 0xffff, v226
	v_and_or_b32 v22, v222, s64, v6
	v_lshrrev_b32_e32 v6, 16, v226
	v_lshl_or_b32 v4, v222, 16, v4
	v_lshl_or_b32 v5, v252, 16, v5
	v_and_or_b32 v23, v252, s64, v6
	ds_write2_b64 v34, v[4:5], v[22:23] offset0:72 offset1:90
	v_and_b32_e32 v4, 0xffff, v219
	v_and_b32_e32 v5, 0xffff, v227
	v_lshrrev_b32_e32 v6, 16, v219
	v_lshrrev_b32_e32 v7, 16, v227
	v_lshl_or_b32 v4, v223, 16, v4
	v_lshl_or_b32 v5, v253, 16, v5
	v_and_or_b32 v6, v223, s64, v6
	v_and_or_b32 v7, v253, s64, v7
	ds_write2_b64 v34, v[4:5], v[6:7] offset0:108 offset1:126
	s_waitcnt lgkmcnt(0)
	s_barrier
	ds_read_b128 v[4:7], v120 offset:36864
	v_mov_b32_e32 v22, v16
	v_mov_b32_e32 v23, v48
	v_mov_b32_e32 v34, v32
	v_mov_b32_e32 v48, v17
	s_waitcnt lgkmcnt(0)
	v_mov_b32_e32 v30, v4
	v_mov_b32_e32 v31, v6
	v_pk_mul_f32 v[22:23], v[22:23], v[30:31]
	v_mov_b32_e32 v6, v5
	v_pk_mul_f32 v[4:5], v[34:35], v[6:7]
	v_and_b32_sdwa v16, v23, v146 dst_sel:DWORD dst_unused:UNUSED_PAD src0_sel:WORD_1 src1_sel:DWORD
	v_and_b32_sdwa v18, v22, v146 dst_sel:DWORD dst_unused:UNUSED_PAD src0_sel:WORD_1 src1_sel:DWORD
	v_add3_u32 v18, v22, v18, s81
	v_add3_u32 v16, v23, v16, s81
	v_and_b32_sdwa v22, v5, v146 dst_sel:DWORD dst_unused:UNUSED_PAD src0_sel:WORD_1 src1_sel:DWORD
	v_and_b32_sdwa v23, v4, v146 dst_sel:DWORD dst_unused:UNUSED_PAD src0_sel:WORD_1 src1_sel:DWORD
	v_add3_u32 v5, v5, v22, s81
	v_add3_u32 v4, v4, v23, s81
	v_mov_b32_e32 v34, v36
	v_mov_b32_e32 v35, v14
	v_and_b32_e32 v5, 0xffff0000, v5
	v_and_b32_e32 v4, 0xffff0000, v4
	v_mov_b32_e32 v22, v12
	v_mov_b32_e32 v23, v50
	v_pk_mul_f32 v[34:35], v[34:35], v[6:7]
	v_or_b32_sdwa v5, v5, v16 dst_sel:DWORD dst_unused:UNUSED_PAD src0_sel:DWORD src1_sel:WORD_1
	v_or_b32_sdwa v4, v4, v18 dst_sel:DWORD dst_unused:UNUSED_PAD src0_sel:DWORD src1_sel:WORD_1
	v_pk_mul_f32 v[22:23], v[22:23], v[30:31]
	v_and_b32_sdwa v16, v35, v146 dst_sel:DWORD dst_unused:UNUSED_PAD src0_sel:WORD_1 src1_sel:DWORD
	v_and_b32_sdwa v18, v34, v146 dst_sel:DWORD dst_unused:UNUSED_PAD src0_sel:WORD_1 src1_sel:DWORD
	v_and_b32_sdwa v12, v23, v146 dst_sel:DWORD dst_unused:UNUSED_PAD src0_sel:WORD_1 src1_sel:DWORD
	v_and_b32_sdwa v14, v22, v146 dst_sel:DWORD dst_unused:UNUSED_PAD src0_sel:WORD_1 src1_sel:DWORD
	v_add3_u32 v16, v35, v16, s81
	v_add3_u32 v18, v34, v18, s81
	v_add3_u32 v14, v22, v14, s81
	v_add3_u32 v12, v23, v12, s81
	v_and_b32_e32 v16, 0xffff0000, v16
	v_and_b32_e32 v18, 0xffff0000, v18
	v_or_b32_sdwa v23, v16, v12 dst_sel:DWORD dst_unused:UNUSED_PAD src0_sel:DWORD src1_sel:WORD_1
	v_or_b32_sdwa v22, v18, v14 dst_sel:DWORD dst_unused:UNUSED_PAD src0_sel:DWORD src1_sel:WORD_1
	ds_write2_b64 v142, v[4:5], v[22:23] offset1:18
	v_pk_mul_f32 v[4:5], v[48:49], v[30:31]
	v_mov_b32_e32 v18, v33
	v_pk_mul_f32 v[16:17], v[18:19], v[6:7]
	v_and_b32_sdwa v12, v5, v146 dst_sel:DWORD dst_unused:UNUSED_PAD src0_sel:WORD_1 src1_sel:DWORD
	v_and_b32_sdwa v14, v4, v146 dst_sel:DWORD dst_unused:UNUSED_PAD src0_sel:WORD_1 src1_sel:DWORD
	v_add3_u32 v4, v4, v14, s81
	v_add3_u32 v5, v5, v12, s81
	v_and_b32_sdwa v12, v17, v146 dst_sel:DWORD dst_unused:UNUSED_PAD src0_sel:WORD_1 src1_sel:DWORD
	v_and_b32_sdwa v14, v16, v146 dst_sel:DWORD dst_unused:UNUSED_PAD src0_sel:WORD_1 src1_sel:DWORD
	v_add3_u32 v12, v17, v12, s81
	v_add3_u32 v14, v16, v14, s81
	v_and_b32_e32 v12, 0xffff0000, v12
	v_and_b32_e32 v14, 0xffff0000, v14
	v_mov_b32_e32 v50, v13
	v_or_b32_sdwa v5, v12, v5 dst_sel:DWORD dst_unused:UNUSED_PAD src0_sel:DWORD src1_sel:WORD_1
	v_or_b32_sdwa v4, v14, v4 dst_sel:DWORD dst_unused:UNUSED_PAD src0_sel:DWORD src1_sel:WORD_1
	v_pk_mul_f32 v[12:13], v[50:51], v[30:31]
	v_mov_b32_e32 v14, v37
	v_pk_mul_f32 v[14:15], v[14:15], v[6:7]
	v_and_b32_sdwa v16, v13, v146 dst_sel:DWORD dst_unused:UNUSED_PAD src0_sel:WORD_1 src1_sel:DWORD
	v_and_b32_sdwa v17, v12, v146 dst_sel:DWORD dst_unused:UNUSED_PAD src0_sel:WORD_1 src1_sel:DWORD
	v_add3_u32 v12, v12, v17, s81
	v_add3_u32 v13, v13, v16, s81
	v_and_b32_sdwa v16, v15, v146 dst_sel:DWORD dst_unused:UNUSED_PAD src0_sel:WORD_1 src1_sel:DWORD
	v_and_b32_sdwa v17, v14, v146 dst_sel:DWORD dst_unused:UNUSED_PAD src0_sel:WORD_1 src1_sel:DWORD
	v_add3_u32 v15, v15, v16, s81
	v_add3_u32 v14, v14, v17, s81
	v_and_b32_e32 v15, 0xffff0000, v15
	v_and_b32_e32 v14, 0xffff0000, v14
	v_or_b32_sdwa v13, v15, v13 dst_sel:DWORD dst_unused:UNUSED_PAD src0_sel:DWORD src1_sel:WORD_1
	v_or_b32_sdwa v12, v14, v12 dst_sel:DWORD dst_unused:UNUSED_PAD src0_sel:DWORD src1_sel:WORD_1
; __device__ __forceinline__ unsigned pk2(float lo, float hi) { return f2bf(lo) | (f2bf(hi) << 16); }
; __device__ __forceinline__ void m1_phase(const Params& p, unsigned char* ldsg, int G) {
;     ...
;             for (int e = 0; e < 8; ++e) { u32x2 o; o.x = pk2(kk[0][e] * w4[0], kk[1][e] * w4[1]); o.y = pk2(kk[2][e] * w4[2], kk[3][e] * w4[3]); *(u32x2*)(KT + tsw(cgp * 8 + e, l0)) = o; }
;         }
;         __syncthreads();
;         {
;             bf16x8 av[2][2];
; #pragma unroll
;             for (int mi = 0; mi < 2; ++mi)
; #pragma unroll
;                 for (int ks = 0; ks < 2; ++ks) av[mi][ks] = *(const bf16x8*)(VT + tsw(16 * (2 * hw + mi) + fr, ks * 32 + fq * 8));
; #pragma unroll
;             for (int nt = 0; nt < 8; ++nt) {
;                 bf16x8 bk[2];
; #pragma unroll
;                 for (int ks = 0; ks < 2; ++ks) bk[ks] = *(const bf16x8*)(KT + tsw(16 * nt + fr, ks * 32 + fq * 8));
; #pragma unroll
;                 for (int mi = 0; mi < 2; ++mi) {
;                     f32x4 acc = (f32x4){0.f, 0.f, 0.f, 0.f};
; #pragma unroll
;                     for (int ks = 0; ks < 2; ++ks) acc = __builtin_amdgcn_mfma_f32_16x16x32_bf16(bk[ks], av[mi][ks], acc, 0, 0, 0);
;                     u32x2 o; o.x = pk2(acc[0], acc[1]); o.y = pk2(acc[2], acc[3]);
;                     { const int vd = 16 * (2 * hw + mi) + fr; *(u32x2*)(DCB + ((size_t)((h * 64 + (vd >> 1)) * NCH + c) << 8) + (vd & 1) * 128 + 16 * nt + fq * 4) = o; }
	ds_write2_b64 v142, v[4:5], v[12:13] offset0:36 offset1:54
	v_mov_b32_e32 v4, v8
	v_mov_b32_e32 v5, v26
	v_pk_mul_f32 v[4:5], v[4:5], v[30:31]
	v_mov_b32_e32 v12, v28
	v_mov_b32_e32 v13, v10
	v_pk_mul_f32 v[12:13], v[12:13], v[6:7]
	v_and_b32_sdwa v8, v5, v146 dst_sel:DWORD dst_unused:UNUSED_PAD src0_sel:WORD_1 src1_sel:DWORD
	v_and_b32_sdwa v10, v4, v146 dst_sel:DWORD dst_unused:UNUSED_PAD src0_sel:WORD_1 src1_sel:DWORD
	v_add3_u32 v4, v4, v10, s81
	v_add3_u32 v5, v5, v8, s81
	v_and_b32_sdwa v8, v13, v146 dst_sel:DWORD dst_unused:UNUSED_PAD src0_sel:WORD_1 src1_sel:DWORD
	v_and_b32_sdwa v10, v12, v146 dst_sel:DWORD dst_unused:UNUSED_PAD src0_sel:WORD_1 src1_sel:DWORD
	v_add3_u32 v8, v13, v8, s81
	v_add3_u32 v10, v12, v10, s81
	v_mov_b32_e32 v14, v20
	v_mov_b32_e32 v15, v2
	v_and_b32_e32 v8, 0xffff0000, v8
	v_and_b32_e32 v10, 0xffff0000, v10
	v_mov_b32_e32 v12, v0
	v_mov_b32_e32 v13, v24
	v_pk_mul_f32 v[14:15], v[14:15], v[6:7]
	v_or_b32_sdwa v5, v8, v5 dst_sel:DWORD dst_unused:UNUSED_PAD src0_sel:DWORD src1_sel:WORD_1
	v_or_b32_sdwa v4, v10, v4 dst_sel:DWORD dst_unused:UNUSED_PAD src0_sel:DWORD src1_sel:WORD_1
	v_pk_mul_f32 v[12:13], v[12:13], v[30:31]
	v_and_b32_sdwa v8, v15, v146 dst_sel:DWORD dst_unused:UNUSED_PAD src0_sel:WORD_1 src1_sel:DWORD
	v_and_b32_sdwa v10, v14, v146 dst_sel:DWORD dst_unused:UNUSED_PAD src0_sel:WORD_1 src1_sel:DWORD
	v_and_b32_sdwa v0, v13, v146 dst_sel:DWORD dst_unused:UNUSED_PAD src0_sel:WORD_1 src1_sel:DWORD
	v_and_b32_sdwa v2, v12, v146 dst_sel:DWORD dst_unused:UNUSED_PAD src0_sel:WORD_1 src1_sel:DWORD
	v_add3_u32 v8, v15, v8, s81
	v_add3_u32 v10, v14, v10, s81
	v_add3_u32 v2, v12, v2, s81
	v_add3_u32 v0, v13, v0, s81
	v_and_b32_e32 v8, 0xffff0000, v8
	v_and_b32_e32 v10, 0xffff0000, v10
	v_or_b32_sdwa v13, v8, v0 dst_sel:DWORD dst_unused:UNUSED_PAD src0_sel:DWORD src1_sel:WORD_1
	v_or_b32_sdwa v12, v10, v2 dst_sel:DWORD dst_unused:UNUSED_PAD src0_sel:DWORD src1_sel:WORD_1
	v_mov_b32_e32 v26, v9
	ds_write2_b64 v142, v[4:5], v[12:13] offset0:72 offset1:90
	v_pk_mul_f32 v[4:5], v[26:27], v[30:31]
	v_mov_b32_e32 v10, v29
	v_pk_mul_f32 v[8:9], v[10:11], v[6:7]
	v_and_b32_sdwa v0, v5, v146 dst_sel:DWORD dst_unused:UNUSED_PAD src0_sel:WORD_1 src1_sel:DWORD
	v_and_b32_sdwa v2, v4, v146 dst_sel:DWORD dst_unused:UNUSED_PAD src0_sel:WORD_1 src1_sel:DWORD
	v_add3_u32 v2, v4, v2, s81
	v_add3_u32 v0, v5, v0, s81
	v_and_b32_sdwa v4, v9, v146 dst_sel:DWORD dst_unused:UNUSED_PAD src0_sel:WORD_1 src1_sel:DWORD
	v_and_b32_sdwa v5, v8, v146 dst_sel:DWORD dst_unused:UNUSED_PAD src0_sel:WORD_1 src1_sel:DWORD
	v_add3_u32 v4, v9, v4, s81
	v_add3_u32 v5, v8, v5, s81
	v_and_b32_e32 v4, 0xffff0000, v4
	v_and_b32_e32 v8, 0xffff0000, v5
	v_mov_b32_e32 v24, v1
	v_or_b32_sdwa v5, v4, v0 dst_sel:DWORD dst_unused:UNUSED_PAD src0_sel:DWORD src1_sel:WORD_1
	v_or_b32_sdwa v4, v8, v2 dst_sel:DWORD dst_unused:UNUSED_PAD src0_sel:DWORD src1_sel:WORD_1
	v_pk_mul_f32 v[0:1], v[24:25], v[30:31]
	v_mov_b32_e32 v2, v21
	v_pk_mul_f32 v[2:3], v[2:3], v[6:7]
	v_and_b32_sdwa v6, v1, v146 dst_sel:DWORD dst_unused:UNUSED_PAD src0_sel:WORD_1 src1_sel:DWORD
	v_and_b32_sdwa v7, v0, v146 dst_sel:DWORD dst_unused:UNUSED_PAD src0_sel:WORD_1 src1_sel:DWORD
	v_add3_u32 v0, v0, v7, s81
	v_add3_u32 v1, v1, v6, s81
	v_and_b32_sdwa v6, v3, v146 dst_sel:DWORD dst_unused:UNUSED_PAD src0_sel:WORD_1 src1_sel:DWORD
	v_and_b32_sdwa v7, v2, v146 dst_sel:DWORD dst_unused:UNUSED_PAD src0_sel:WORD_1 src1_sel:DWORD
	v_add3_u32 v3, v3, v6, s81
	v_add3_u32 v2, v2, v7, s81
	v_and_b32_e32 v3, 0xffff0000, v3
	v_and_b32_e32 v2, 0xffff0000, v2
	v_or_b32_sdwa v1, v3, v1 dst_sel:DWORD dst_unused:UNUSED_PAD src0_sel:DWORD src1_sel:WORD_1
	v_or_b32_sdwa v0, v2, v0 dst_sel:DWORD dst_unused:UNUSED_PAD src0_sel:DWORD src1_sel:WORD_1
	ds_write2_b64 v142, v[4:5], v[0:1] offset0:108 offset1:126
	s_waitcnt lgkmcnt(0)
	s_barrier
	ds_read_b128 v[16:19], v125
	ds_read_b128 v[20:23], v126
	ds_read_b128 v[12:15], v121 offset:18432
	ds_read_b128 v[8:11], v122 offset:18432
	ds_read_b128 v[4:7], v123 offset:18432
	ds_read_b128 v[0:3], v124 offset:18432
	ds_read_b128 v[24:27], v125 offset:9216
	s_waitcnt lgkmcnt(4)
	v_mfma_f32_16x16x32_bf16 v[28:31], v[16:19], v[12:15], 0
	ds_read_b128 v[32:35], v126 offset:9216
	v_ashrrev_i32_e32 v39, 31, v38
	s_waitcnt lgkmcnt(4)
	v_mfma_f32_16x16x32_bf16 v[28:31], v[20:23], v[8:11], v[28:31]
	s_nop 7
	v_bfe_u32 v36, v28, 16, 1
	v_add3_u32 v28, v28, v36, s81
	v_bfe_u32 v36, v29, 16, 1
	v_lshrrev_b32_e32 v28, 16, v28
	v_add3_u32 v29, v29, v36, s81
	v_and_or_b32 v36, v29, s64, v28
	v_bfe_u32 v28, v30, 16, 1
	v_add3_u32 v28, v30, v28, s81
	v_bfe_u32 v29, v31, 16, 1
	v_lshrrev_b32_e32 v28, 16, v28
	v_add3_u32 v29, v31, v29, s81
	v_and_or_b32 v37, v29, s64, v28
	s_waitcnt lgkmcnt(3)
	v_mfma_f32_16x16x32_bf16 v[28:31], v[16:19], v[4:7], 0
	v_lshlrev_b64 v[16:17], 9, v[38:39]
	v_lshl_add_u64 v[16:17], v[70:71], 0, v[16:17]
	global_store_dwordx2 v[16:17], v[36:37], off
	s_waitcnt lgkmcnt(2)
	v_mfma_f32_16x16x32_bf16 v[18:21], v[20:23], v[0:3], v[28:31]
	ds_read_b128 v[36:39], v130
	s_nop 1
	ds_read_b128 v[28:31], v129
	s_nop 3
	v_bfe_u32 v22, v18, 16, 1
	v_add3_u32 v18, v18, v22, s81
	v_bfe_u32 v22, v19, 16, 1
	v_lshrrev_b32_e32 v18, 16, v18
	v_add3_u32 v19, v19, v22, s81
	v_and_or_b32 v40, v19, s64, v18
	v_bfe_u32 v18, v20, 16, 1
	v_bfe_u32 v19, v21, 16, 1
	v_add3_u32 v18, v20, v18, s81
	v_add3_u32 v19, v21, v19, s81
	s_waitcnt lgkmcnt(0)
; __device__ __forceinline__ unsigned pk2(float lo, float hi) { return f2bf(lo) | (f2bf(hi) << 16); }
; __device__ __forceinline__ void m1_phase(const Params& p, unsigned char* ldsg, int G) {
;     ...
; #pragma unroll
;             for (int nt = 0; nt < 8; ++nt) {
;                 bf16x8 bk[2];
; #pragma unroll
;                 for (int ks = 0; ks < 2; ++ks) bk[ks] = *(const bf16x8*)(KT + tsw(16 * nt + fr, ks * 32 + fq * 8));
; #pragma unroll
;                 for (int mi = 0; mi < 2; ++mi) {
;                     f32x4 acc = (f32x4){0.f, 0.f, 0.f, 0.f};
; #pragma unroll
;                     for (int ks = 0; ks < 2; ++ks) acc = __builtin_amdgcn_mfma_f32_16x16x32_bf16(bk[ks], av[mi][ks], acc, 0, 0, 0);
;                     u32x2 o; o.x = pk2(acc[0], acc[1]); o.y = pk2(acc[2], acc[3]);
;                     { const int vd = 16 * (2 * hw + mi) + fr; *(u32x2*)(DCB + ((size_t)((h * 64 + (vd >> 1)) * NCH + c) << 8) + (vd & 1) * 128 + 16 * nt + fq * 4) = o; }
;                 }
	v_mfma_f32_16x16x32_bf16 v[20:23], v[28:31], v[12:15], 0
	v_lshrrev_b32_e32 v18, 16, v18
	v_and_or_b32 v41, v19, s64, v18
	v_add_u32_e32 v18, s0, v128
	v_mfma_f32_16x16x32_bf16 v[20:23], v[36:39], v[8:11], v[20:23]
	v_ashrrev_i32_e32 v19, 31, v18
	v_lshlrev_b64 v[18:19], 9, v[18:19]
	v_lshl_add_u64 v[18:19], v[70:71], 0, v[18:19]
	global_store_dwordx2 v[18:19], v[40:41], off
	v_mfma_f32_16x16x32_bf16 v[28:31], v[28:31], v[4:7], 0
	s_nop 2
	v_bfe_u32 v40, v20, 16, 1
	v_add3_u32 v20, v20, v40, s81
	v_bfe_u32 v40, v21, 16, 1
	v_lshrrev_b32_e32 v20, 16, v20
	v_add3_u32 v21, v21, v40, s81
	v_and_or_b32 v20, v21, s64, v20
	v_bfe_u32 v21, v22, 16, 1
	v_add3_u32 v21, v22, v21, s81
	v_bfe_u32 v22, v23, 16, 1
	v_lshrrev_b32_e32 v21, 16, v21
	v_add3_u32 v22, v23, v22, s81
	v_and_or_b32 v21, v22, s64, v21
	global_store_dwordx2 v[16:17], v[20:21], off offset:32
	v_mfma_f32_16x16x32_bf16 v[20:23], v[36:39], v[0:3], v[28:31]
	s_nop 7
	v_bfe_u32 v28, v20, 16, 1
	v_add3_u32 v20, v20, v28, s81
	ds_read_b128 v[28:31], v131
	v_bfe_u32 v36, v21, 16, 1
	v_add3_u32 v21, v21, v36, s81
	ds_read_b128 v[36:39], v132
	v_lshrrev_b32_e32 v20, 16, v20
	v_and_or_b32 v20, v21, s64, v20
	v_bfe_u32 v21, v22, 16, 1
	s_waitcnt lgkmcnt(1)
	v_mfma_f32_16x16x32_bf16 v[40:43], v[28:31], v[12:15], 0
	v_add3_u32 v21, v22, v21, s81
	v_bfe_u32 v22, v23, 16, 1
	v_lshrrev_b32_e32 v21, 16, v21
	v_add3_u32 v22, v23, v22, s81
	v_and_or_b32 v21, v22, s64, v21
	global_store_dwordx2 v[18:19], v[20:21], off offset:32
	s_waitcnt lgkmcnt(0)
	v_mfma_f32_16x16x32_bf16 v[20:23], v[36:39], v[8:11], v[40:43]
	v_mfma_f32_16x16x32_bf16 v[28:31], v[28:31], v[4:7], 0
	s_nop 6
	v_bfe_u32 v40, v20, 16, 1
	v_add3_u32 v20, v20, v40, s81
	v_bfe_u32 v40, v21, 16, 1
	v_lshrrev_b32_e32 v20, 16, v20
	v_add3_u32 v21, v21, v40, s81
	v_and_or_b32 v20, v21, s64, v20
	v_bfe_u32 v21, v22, 16, 1
	v_add3_u32 v21, v22, v21, s81
	v_bfe_u32 v22, v23, 16, 1
	v_lshrrev_b32_e32 v21, 16, v21
	v_add3_u32 v22, v23, v22, s81
	v_and_or_b32 v21, v22, s64, v21
	global_store_dwordx2 v[16:17], v[20:21], off offset:64
	v_mfma_f32_16x16x32_bf16 v[20:23], v[36:39], v[0:3], v[28:31]
	s_nop 7
	v_bfe_u32 v28, v20, 16, 1
	v_add3_u32 v20, v20, v28, s81
	ds_read_b128 v[28:31], v133
	v_bfe_u32 v36, v21, 16, 1
	v_add3_u32 v21, v21, v36, s81
	ds_read_b128 v[36:39], v134
	v_lshrrev_b32_e32 v20, 16, v20
	v_and_or_b32 v20, v21, s64, v20
	v_bfe_u32 v21, v22, 16, 1
	s_waitcnt lgkmcnt(1)
	v_mfma_f32_16x16x32_bf16 v[40:43], v[28:31], v[12:15], 0
	v_add3_u32 v21, v22, v21, s81
	v_bfe_u32 v22, v23, 16, 1
	v_lshrrev_b32_e32 v21, 16, v21
	v_add3_u32 v22, v23, v22, s81
	v_and_or_b32 v21, v22, s64, v21
	global_store_dwordx2 v[18:19], v[20:21], off offset:64
	s_waitcnt lgkmcnt(0)
	v_mfma_f32_16x16x32_bf16 v[20:23], v[36:39], v[8:11], v[40:43]
	v_mfma_f32_16x16x32_bf16 v[28:31], v[28:31], v[4:7], 0
	s_nop 6
	v_bfe_u32 v40, v20, 16, 1
	v_add3_u32 v20, v20, v40, s81
	v_bfe_u32 v40, v21, 16, 1
	v_lshrrev_b32_e32 v20, 16, v20
	v_add3_u32 v21, v21, v40, s81
	v_and_or_b32 v20, v21, s64, v20
	v_bfe_u32 v21, v22, 16, 1
	v_add3_u32 v21, v22, v21, s81
	v_bfe_u32 v22, v23, 16, 1
	v_lshrrev_b32_e32 v21, 16, v21
	v_add3_u32 v22, v23, v22, s81
	v_and_or_b32 v21, v22, s64, v21
	global_store_dwordx2 v[16:17], v[20:21], off offset:96
	v_mfma_f32_16x16x32_bf16 v[20:23], v[36:39], v[0:3], v[28:31]
	s_nop 7
	v_bfe_u32 v28, v20, 16, 1
	v_add3_u32 v20, v20, v28, s81
	v_bfe_u32 v28, v21, 16, 1
	v_lshrrev_b32_e32 v20, 16, v20
	v_add3_u32 v21, v21, v28, s81
	v_and_or_b32 v20, v21, s64, v20
	v_bfe_u32 v21, v22, 16, 1
	v_mfma_f32_16x16x32_bf16 v[28:31], v[24:27], v[12:15], 0
	v_add3_u32 v21, v22, v21, s81
	v_bfe_u32 v22, v23, 16, 1
	v_lshrrev_b32_e32 v21, 16, v21
	v_add3_u32 v22, v23, v22, s81
	v_and_or_b32 v21, v22, s64, v21
	global_store_dwordx2 v[18:19], v[20:21], off offset:96
	v_mfma_f32_16x16x32_bf16 v[20:23], v[32:35], v[8:11], v[28:31]
	v_mfma_f32_16x16x32_bf16 v[24:27], v[24:27], v[4:7], 0
	s_nop 6
	v_bfe_u32 v28, v20, 16, 1
	v_add3_u32 v20, v20, v28, s81
	v_bfe_u32 v28, v21, 16, 1
	v_lshrrev_b32_e32 v20, 16, v20
	v_add3_u32 v21, v21, v28, s81
	v_and_or_b32 v20, v21, s64, v20
	v_bfe_u32 v21, v22, 16, 1
	v_add3_u32 v21, v22, v21, s81
	v_bfe_u32 v22, v23, 16, 1
	v_lshrrev_b32_e32 v21, 16, v21
	v_add3_u32 v22, v23, v22, s81
	v_and_or_b32 v21, v22, s64, v21
	global_store_dwordx2 v[16:17], v[20:21], off offset:128
	v_mfma_f32_16x16x32_bf16 v[20:23], v[32:35], v[0:3], v[24:27]
	s_nop 7
	v_bfe_u32 v24, v20, 16, 1
	v_add3_u32 v20, v20, v24, s81
	ds_read_b128 v[24:27], v135
	v_bfe_u32 v28, v21, 16, 1
	v_add3_u32 v21, v21, v28, s81
	ds_read_b128 v[28:31], v136
	v_lshrrev_b32_e32 v20, 16, v20
	v_and_or_b32 v20, v21, s64, v20
	v_bfe_u32 v21, v22, 16, 1
	s_waitcnt lgkmcnt(1)
	v_mfma_f32_16x16x32_bf16 v[32:35], v[24:27], v[12:15], 0
	v_add3_u32 v21, v22, v21, s81
	v_bfe_u32 v22, v23, 16, 1
	v_lshrrev_b32_e32 v21, 16, v21
	v_add3_u32 v22, v23, v22, s81
	v_and_or_b32 v21, v22, s64, v21
	global_store_dwordx2 v[18:19], v[20:21], off offset:128
	s_waitcnt lgkmcnt(0)
	v_mfma_f32_16x16x32_bf16 v[20:23], v[28:31], v[8:11], v[32:35]
	v_mfma_f32_16x16x32_bf16 v[24:27], v[24:27], v[4:7], 0
	s_nop 6
	v_bfe_u32 v32, v20, 16, 1
	v_add3_u32 v20, v20, v32, s81
	v_bfe_u32 v32, v21, 16, 1
	v_lshrrev_b32_e32 v20, 16, v20
	v_add3_u32 v21, v21, v32, s81
	v_and_or_b32 v20, v21, s64, v20
	v_bfe_u32 v21, v22, 16, 1
	v_add3_u32 v21, v22, v21, s81
	v_bfe_u32 v22, v23, 16, 1
	v_lshrrev_b32_e32 v21, 16, v21
	v_add3_u32 v22, v23, v22, s81
	v_and_or_b32 v21, v22, s64, v21
	global_store_dwordx2 v[16:17], v[20:21], off offset:160
	v_mfma_f32_16x16x32_bf16 v[20:23], v[28:31], v[0:3], v[24:27]
	s_nop 7
	v_bfe_u32 v24, v20, 16, 1
	v_add3_u32 v20, v20, v24, s81
	ds_read_b128 v[24:27], v137
	v_bfe_u32 v28, v21, 16, 1
	v_add3_u32 v21, v21, v28, s81
	ds_read_b128 v[28:31], v138
	v_lshrrev_b32_e32 v20, 16, v20
	v_and_or_b32 v20, v21, s64, v20
	v_bfe_u32 v21, v22, 16, 1
	s_waitcnt lgkmcnt(1)
; __device__ __forceinline__ unsigned pk2(float lo, float hi) { return f2bf(lo) | (f2bf(hi) << 16); }
; __device__ __forceinline__ float bf2f(unsigned b) { return __uint_as_float(b << 16); }
; __device__ __forceinline__ void m1_phase(const Params& p, unsigned char* ldsg, int G) {
;     ...
;             for (int nt = 0; nt < 8; ++nt) {
;                 bf16x8 bk[2];
; #pragma unroll
;                 for (int ks = 0; ks < 2; ++ks) bk[ks] = *(const bf16x8*)(KT + tsw(16 * nt + fr, ks * 32 + fq * 8));
; #pragma unroll
;                 for (int mi = 0; mi < 2; ++mi) {
;                     f32x4 acc = (f32x4){0.f, 0.f, 0.f, 0.f};
; #pragma unroll
;                     for (int ks = 0; ks < 2; ++ks) acc = __builtin_amdgcn_mfma_f32_16x16x32_bf16(bk[ks], av[mi][ks], acc, 0, 0, 0);
;                     u32x2 o; o.x = pk2(acc[0], acc[1]); o.y = pk2(acc[2], acc[3]);
;                     { const int vd = 16 * (2 * hw + mi) + fr; *(u32x2*)(DCB + ((size_t)((h * 64 + (vd >> 1)) * NCH + c) << 8) + (vd & 1) * 128 + 16 * nt + fq * 4) = o; }
;                 }
;             }
;             if (htid < 128) { float s = 0.f;
; #pragma unroll 8
;                 for (int l = 0; l < 64; ++l) s += bf2f(KT[htid * TP + l]);
;                 DN[(size_t)(h * NCH + c) * 128 + htid] = s; }
	v_mfma_f32_16x16x32_bf16 v[32:35], v[24:27], v[12:15], 0
	v_add3_u32 v21, v22, v21, s81
	v_bfe_u32 v22, v23, 16, 1
	v_lshrrev_b32_e32 v21, 16, v21
	v_add3_u32 v22, v23, v22, s81
	v_and_or_b32 v21, v22, s64, v21
	global_store_dwordx2 v[18:19], v[20:21], off offset:160
	s_waitcnt lgkmcnt(0)
	v_mfma_f32_16x16x32_bf16 v[20:23], v[28:31], v[8:11], v[32:35]
	v_mfma_f32_16x16x32_bf16 v[24:27], v[24:27], v[4:7], 0
	s_nop 6
	v_bfe_u32 v32, v20, 16, 1
	v_add3_u32 v20, v20, v32, s81
	v_bfe_u32 v32, v21, 16, 1
	v_lshrrev_b32_e32 v20, 16, v20
	v_add3_u32 v21, v21, v32, s81
	v_and_or_b32 v20, v21, s64, v20
	v_bfe_u32 v21, v22, 16, 1
	v_add3_u32 v21, v22, v21, s81
	v_bfe_u32 v22, v23, 16, 1
	v_lshrrev_b32_e32 v21, 16, v21
	v_add3_u32 v22, v23, v22, s81
	v_and_or_b32 v21, v22, s64, v21
	global_store_dwordx2 v[16:17], v[20:21], off offset:192
	v_mfma_f32_16x16x32_bf16 v[20:23], v[28:31], v[0:3], v[24:27]
	s_nop 7
	v_bfe_u32 v24, v20, 16, 1
	v_add3_u32 v20, v20, v24, s81
	ds_read_b128 v[24:27], v139
	v_bfe_u32 v28, v21, 16, 1
	v_add3_u32 v21, v21, v28, s81
	ds_read_b128 v[28:31], v140
	s_waitcnt lgkmcnt(1)
	v_mfma_f32_16x16x32_bf16 v[12:15], v[24:27], v[12:15], 0
	v_lshrrev_b32_e32 v20, 16, v20
	v_and_or_b32 v20, v21, s64, v20
	v_bfe_u32 v21, v22, 16, 1
	v_mfma_f32_16x16x32_bf16 v[4:7], v[24:27], v[4:7], 0
	v_add3_u32 v21, v22, v21, s81
	v_bfe_u32 v22, v23, 16, 1
	v_lshrrev_b32_e32 v21, 16, v21
	s_waitcnt lgkmcnt(0)
	v_mfma_f32_16x16x32_bf16 v[8:11], v[28:31], v[8:11], v[12:15]
	v_add3_u32 v22, v23, v22, s81
	v_and_or_b32 v21, v22, s64, v21
	global_store_dwordx2 v[18:19], v[20:21], off offset:192
	v_mfma_f32_16x16x32_bf16 v[0:3], v[28:31], v[0:3], v[4:7]
	s_nop 3
	v_bfe_u32 v12, v8, 16, 1
	s_nop 2
	v_bfe_u32 v4, v0, 16, 1
	v_add3_u32 v8, v8, v12, s81
	v_bfe_u32 v12, v9, 16, 1
	v_add3_u32 v0, v0, v4, s81
	v_bfe_u32 v4, v1, 16, 1
	v_lshrrev_b32_e32 v8, 16, v8
	v_add3_u32 v9, v9, v12, s81
	v_lshrrev_b32_e32 v0, 16, v0
	v_add3_u32 v1, v1, v4, s81
	v_and_or_b32 v8, v9, s64, v8
	v_bfe_u32 v9, v10, 16, 1
	v_and_or_b32 v0, v1, s64, v0
	v_bfe_u32 v1, v2, 16, 1
	v_add3_u32 v9, v10, v9, s81
	v_bfe_u32 v10, v11, 16, 1
	v_add3_u32 v1, v2, v1, s81
	v_bfe_u32 v2, v3, 16, 1
	v_lshrrev_b32_e32 v9, 16, v9
	v_add3_u32 v10, v11, v10, s81
	v_lshrrev_b32_e32 v1, 16, v1
	v_add3_u32 v2, v3, v2, s81
	v_and_or_b32 v9, v10, s64, v9
	v_and_or_b32 v1, v2, s64, v1
	global_store_dwordx2 v[16:17], v[8:9], off offset:224
	global_store_dwordx2 v[18:19], v[0:1], off offset:224
	s_and_saveexec_b64 s[0:1], s[20:21]
	s_cbranch_execz .LBB0_610
	ds_read_b128 v[188:191], v93
	ds_read_b128 v[192:195], v93 offset:16
	ds_read_b128 v[196:199], v93 offset:32
	ds_read_b128 v[200:203], v93 offset:48
	ds_read_b128 v[204:207], v93 offset:64
	ds_read_b128 v[208:211], v93 offset:80
	ds_read_b128 v[212:215], v93 offset:96
	ds_read_b128 v[216:219], v93 offset:112
	v_mov_b32_e32 v0, 0
	v_mov_b32_e32 v1, 0
	v_mov_b32_e32 v2, 0
	v_mov_b32_e32 v3, 0
	s_waitcnt lgkmcnt(7)
	v_lshlrev_b32_e32 v4, 16, v188
	v_lshlrev_b32_e32 v5, 16, v189
	v_and_b32_e32 v188, 0xffff0000, v188
	v_and_b32_e32 v189, 0xffff0000, v189
	v_lshlrev_b32_e32 v6, 16, v190
	v_lshlrev_b32_e32 v7, 16, v191
	v_and_b32_e32 v190, 0xffff0000, v190
	v_and_b32_e32 v191, 0xffff0000, v191
	v_pk_add_f32 v[0:1], v[0:1], v[4:5]
	v_pk_add_f32 v[2:3], v[2:3], v[188:189]
	v_pk_add_f32 v[0:1], v[0:1], v[6:7]
	v_pk_add_f32 v[2:3], v[2:3], v[190:191]
	s_waitcnt lgkmcnt(6)
	v_lshlrev_b32_e32 v4, 16, v192
	v_lshlrev_b32_e32 v5, 16, v193
	v_and_b32_e32 v192, 0xffff0000, v192
	v_and_b32_e32 v193, 0xffff0000, v193
	v_lshlrev_b32_e32 v6, 16, v194
	v_lshlrev_b32_e32 v7, 16, v195
	v_and_b32_e32 v194, 0xffff0000, v194
	v_and_b32_e32 v195, 0xffff0000, v195
	v_pk_add_f32 v[0:1], v[0:1], v[4:5]
	v_pk_add_f32 v[2:3], v[2:3], v[192:193]
	v_pk_add_f32 v[0:1], v[0:1], v[6:7]
	v_pk_add_f32 v[2:3], v[2:3], v[194:195]
	s_waitcnt lgkmcnt(5)
	v_lshlrev_b32_e32 v4, 16, v196
	v_lshlrev_b32_e32 v5, 16, v197
	v_and_b32_e32 v196, 0xffff0000, v196
	v_and_b32_e32 v197, 0xffff0000, v197
	v_lshlrev_b32_e32 v6, 16, v198
	v_lshlrev_b32_e32 v7, 16, v199
	v_and_b32_e32 v198, 0xffff0000, v198
	v_and_b32_e32 v199, 0xffff0000, v199
	v_pk_add_f32 v[0:1], v[0:1], v[4:5]
	v_pk_add_f32 v[2:3], v[2:3], v[196:197]
	v_pk_add_f32 v[0:1], v[0:1], v[6:7]
	v_pk_add_f32 v[2:3], v[2:3], v[198:199]
	s_waitcnt lgkmcnt(4)
	v_lshlrev_b32_e32 v4, 16, v200
	v_lshlrev_b32_e32 v5, 16, v201
	v_and_b32_e32 v200, 0xffff0000, v200
	v_and_b32_e32 v201, 0xffff0000, v201
	v_lshlrev_b32_e32 v6, 16, v202
	v_lshlrev_b32_e32 v7, 16, v203
	v_and_b32_e32 v202, 0xffff0000, v202
	v_and_b32_e32 v203, 0xffff0000, v203
	v_pk_add_f32 v[0:1], v[0:1], v[4:5]
	v_pk_add_f32 v[2:3], v[2:3], v[200:201]
	v_pk_add_f32 v[0:1], v[0:1], v[6:7]
	v_pk_add_f32 v[2:3], v[2:3], v[202:203]
	s_waitcnt lgkmcnt(3)
	v_lshlrev_b32_e32 v4, 16, v204
	v_lshlrev_b32_e32 v5, 16, v205
	v_and_b32_e32 v204, 0xffff0000, v204
	v_and_b32_e32 v205, 0xffff0000, v205
	v_lshlrev_b32_e32 v6, 16, v206
	v_lshlrev_b32_e32 v7, 16, v207
	v_and_b32_e32 v206, 0xffff0000, v206
	v_and_b32_e32 v207, 0xffff0000, v207
	v_pk_add_f32 v[0:1], v[0:1], v[4:5]
	v_pk_add_f32 v[2:3], v[2:3], v[204:205]
	v_pk_add_f32 v[0:1], v[0:1], v[6:7]
	v_pk_add_f32 v[2:3], v[2:3], v[206:207]
	s_waitcnt lgkmcnt(2)
	v_lshlrev_b32_e32 v4, 16, v208
	v_lshlrev_b32_e32 v5, 16, v209
	v_and_b32_e32 v208, 0xffff0000, v208
	v_and_b32_e32 v209, 0xffff0000, v209
	v_lshlrev_b32_e32 v6, 16, v210
	v_lshlrev_b32_e32 v7, 16, v211
	v_and_b32_e32 v210, 0xffff0000, v210
	v_and_b32_e32 v211, 0xffff0000, v211
	v_pk_add_f32 v[0:1], v[0:1], v[4:5]
	v_pk_add_f32 v[2:3], v[2:3], v[208:209]
	v_pk_add_f32 v[0:1], v[0:1], v[6:7]
	v_pk_add_f32 v[2:3], v[2:3], v[210:211]
	s_waitcnt lgkmcnt(1)
	v_lshlrev_b32_e32 v4, 16, v212
	v_lshlrev_b32_e32 v5, 16, v213
	v_and_b32_e32 v212, 0xffff0000, v212
	v_and_b32_e32 v213, 0xffff0000, v213
	v_lshlrev_b32_e32 v6, 16, v214
	v_lshlrev_b32_e32 v7, 16, v215
	v_and_b32_e32 v214, 0xffff0000, v214
	v_and_b32_e32 v215, 0xffff0000, v215
	v_pk_add_f32 v[0:1], v[0:1], v[4:5]
	v_pk_add_f32 v[2:3], v[2:3], v[212:213]
	v_pk_add_f32 v[0:1], v[0:1], v[6:7]
	v_pk_add_f32 v[2:3], v[2:3], v[214:215]
	s_waitcnt lgkmcnt(0)
	v_lshlrev_b32_e32 v4, 16, v216
	v_lshlrev_b32_e32 v5, 16, v217
	v_and_b32_e32 v216, 0xffff0000, v216
	v_and_b32_e32 v217, 0xffff0000, v217
	v_lshlrev_b32_e32 v6, 16, v218
	v_lshlrev_b32_e32 v7, 16, v219
	v_and_b32_e32 v218, 0xffff0000, v218
	v_and_b32_e32 v219, 0xffff0000, v219
	v_pk_add_f32 v[0:1], v[0:1], v[4:5]
	v_pk_add_f32 v[2:3], v[2:3], v[216:217]
	v_pk_add_f32 v[0:1], v[0:1], v[6:7]
	v_pk_add_f32 v[2:3], v[2:3], v[218:219]
	v_pk_add_f32 v[0:1], v[0:1], v[2:3]
	s_nop 0
	v_add_f32_e32 v0, v0, v1
	s_lshl_b32 s22, s44, 8
	s_add_i32 s22, s22, s83
	s_ashr_i32 s23, s22, 31
	s_lshl_b64 s[22:23], s[22:23], 9
	v_lshl_add_u64 v[2:3], v[72:73], 0, s[22:23]
	global_store_dword v[2:3], v0, off
	s_branch .LBB0_610

; __device__ __forceinline__ unsigned cvt_pk_bf16(float lo, float hi) { unsigned r; asm volatile("v_cvt_pk_bf16_f32 %0, %1, %2" : "=v"(r) : "v"(lo), "v"(hi)); return r; }
; __device__ __forceinline__ void bf8_to_f32(const u32x4 v, f32x4& lo, f32x4& hi) {
;     lo = (f32x4){__uint_as_float(v.x << 16), __uint_as_float(v.x & 0xffff0000u), __uint_as_float(v.y << 16), __uint_as_float(v.y & 0xffff0000u)};
;     hi = (f32x4){__uint_as_float(v.z << 16), __uint_as_float(v.z & 0xffff0000u), __uint_as_float(v.w << 16), __uint_as_float(v.w & 0xffff0000u)};
; }
;     __device__ __forceinline__ void operator()(const f32x4 (&acc)[2][2][4][2], const Unit& u, int wr, int wc, int fr, int fq) const {
;     ...
;             for (int m = 0; m < 4; ++m) {
;                 const int row = row0 + ai * HALF + m * 16; const size_t off = (size_t)row * DM + col0; float q = 0.f;
; #pragma unroll
;                 for (int bj = 0; bj < 2; ++bj) {
;                     const size_t o2 = off + bj * HALF; f32x4 b0, b1;
;                     if (XI_BF16) bf8_to_f32(xin[0][m][bj], b0, b1); else { b0 = *(const f32x4*)(xi + o2); b1 = *(const f32x4*)(xi + o2 + 4); }
;                     const f32x4 o0 = b0 + acc[ai][bj][m][0] * scale, o1 = b1 + acc[ai][bj][m][1] * scale;
;                     u32x4 w; w.x = cvt_pk_bf16(o0[0], o0[1]); w.y = cvt_pk_bf16(o0[2], o0[3]); w.z = cvt_pk_bf16(o1[0], o1[1]); w.w = cvt_pk_bf16(o1[2], o1[3]);
;                     *(u32x4*)(xb + o2) = w;
;                     q += ((o0[0] * o0[0] + o0[1] * o0[1]) + (o0[2] * o0[2] + o0[3] * o0[3])) + ((o1[0] * o1[0] + o1[1] * o1[1]) + (o1[2] * o1[2] + o1[3] * o1[3]));
;                 }
;                 q += __shfl_xor(q, 16); q += __shfl_xor(q, 32);
;                 if (fq == 0) ssout[(size_t)row * 16 + u.pn * 4 + wc] = q;
.Lalign_p7:
	v_and_b32_e32 v217, 64, v203
	v_xor_b32_e32 v216, 16, v203
	v_add_u32_e32 v217, 64, v217
	v_xor_b32_e32 v218, 32, v203
	v_cmp_lt_i32_e32 vcc, v216, v217
	s_lshl_b32 s24, s0, 2
	s_ashr_i32 s25, s24, 31
	v_cndmask_b32_e32 v219, v203, v216, vcc
	v_cmp_lt_i32_e32 vcc, v218, v217
	v_lshl_add_u64 v[216:217], s[76:77], 0, v[204:205]
	v_lshlrev_b32_e32 v204, 2, v219
	v_cndmask_b32_e32 v224, v203, v218, vcc
	v_lshl_add_u64 v[214:215], v[216:217], 0, v[214:215]
	s_waitcnt vmcnt(0)
	v_lshlrev_b32_e32 v216, 16, v206
	v_and_b32_e32 v217, 0xffff0000, v206
	v_lshlrev_b32_e32 v206, 16, v207
	v_and_b32_e32 v207, 0xffff0000, v207
	v_lshlrev_b32_e32 v218, 16, v208
	v_and_b32_e32 v219, 0xffff0000, v208
	v_lshlrev_b32_e32 v208, 16, v209
	v_and_b32_e32 v209, 0xffff0000, v209
	v_lshlrev_b32_e32 v220, 16, v210
	v_and_b32_e32 v221, 0xffff0000, v210
	v_lshlrev_b32_e32 v210, 16, v211
	v_and_b32_e32 v211, 0xffff0000, v211
	v_lshlrev_b32_e32 v222, 16, v212
	v_and_b32_e32 v223, 0xffff0000, v212
	v_lshlrev_b32_e32 v212, 16, v213
	v_and_b32_e32 v213, 0xffff0000, v213
	v_pk_add_f32 v[126:127], v[126:127], v[206:207]
	v_pk_add_f32 v[124:125], v[124:125], v[216:217]
	v_pk_add_f32 v[122:123], v[122:123], v[208:209]
	v_pk_add_f32 v[120:121], v[120:121], v[218:219]
	v_pk_add_f32 v[118:119], v[118:119], v[210:211]
	v_pk_add_f32 v[116:117], v[116:117], v[220:221]
	v_pk_add_f32 v[206:207], v[114:115], v[212:213]
	v_pk_add_f32 v[208:209], v[112:113], v[222:223]
	v_cvt_pk_bf16_f32 v112, v124, v125
	v_cvt_pk_bf16_f32 v113, v126, v127
	v_mul_f32_e32 v114, v125, v125
	v_mul_f32_e32 v115, v127, v127
	v_mul_f32_e32 v125, v121, v121
	v_mul_f32_e32 v127, v123, v123
	v_mul_f32_e32 v205, v117, v117
	v_mul_f32_e32 v210, v119, v119
	v_mul_f32_e32 v211, v209, v209
	v_mul_f32_e32 v212, v207, v207
	v_fmac_f32_e32 v114, v124, v124
	v_fmac_f32_e32 v115, v126, v126
	v_fmac_f32_e32 v125, v120, v120
	v_fmac_f32_e32 v127, v122, v122
	v_fmac_f32_e32 v205, v116, v116
	v_fmac_f32_e32 v210, v118, v118
	v_fmac_f32_e32 v211, v208, v208
	v_fmac_f32_e32 v212, v206, v206
	v_add_f32_e32 v114, v114, v115
	v_add_f32_e32 v115, v125, v127
	v_add_f32_e32 v124, v205, v210
	v_add_f32_e32 v125, v211, v212
	v_add_f32_e32 v114, v114, v115
	v_add_f32_e32 v115, v124, v125
	v_add_f32_e32 v124, v114, v115
	v_mov_b32_e32 v125, v124
	s_nop 1
	v_permlane16_swap_b32_e32 v124, v125
	v_cvt_pk_bf16_f32 v114, v120, v121
	v_cvt_pk_bf16_f32 v115, v122, v123
	global_store_dwordx4 v[214:215], v[112:115], off
	v_cvt_pk_bf16_f32 v116, v116, v117
	v_cvt_pk_bf16_f32 v117, v118, v119
	v_cvt_pk_bf16_f32 v118, v208, v209
	v_cvt_pk_bf16_f32 v119, v206, v207
	global_store_dwordx4 v[214:215], v[116:119], off offset:256
	s_waitcnt lgkmcnt(0)
	v_add_f32_e32 v113, v124, v125
	v_lshlrev_b32_e32 v112, 2, v224
	v_mov_b32_e32 v114, v113
	s_nop 1
	v_permlane32_swap_b32_e32 v113, v114
	s_and_saveexec_b64 s[26:27], s[8:9]
	s_cbranch_execz .LBB0_1235
	v_lshlrev_b64 v[116:117], 6, v[186:187]
	v_lshl_add_u64 v[116:117], s[12:13], 0, v[116:117]
	v_lshl_add_u64 v[116:117], s[24:25], 2, v[116:117]
	s_lshl_b32 s0, s38, 2
	v_lshl_add_u64 v[116:117], v[116:117], 0, s[0:1]
	s_waitcnt lgkmcnt(0)
	v_add_f32_e32 v113, v113, v114
	global_store_dword v[116:117], v113, off
